# hand-written 256x128 GEMM tile routine (A via LDS-DMA, B fragments direct) for w_out/ff1/ff2; MLA loop pipelined v3
# speedup vs baseline: 1.0614x; 1.0414x over previous
.Lg2_ff2_entry:
	s_waitcnt vmcnt(0) lgkmcnt(0)
	s_barrier
	v_mov_b32_e32 v2, 0x10200
	ds_read_b64 v[2:3], v2
	v_readlane_b32 s0, v246, 0
	v_lshrrev_b32_e32 v4, 6, v163
	v_and_b32_e32 v5, 63, v163
	s_and_b32 s1, s0, 7
	s_lshr_b32 s0, s0, 3
	s_and_b32 s68, s0, 7
	s_lshr_b32 s0, s0, 3
	s_lshl_b32 s0, s0, 3
	s_add_i32 s0, s0, s1
	s_cmp_lt_u32 s0, 32
	s_cselect_b32 s65, 1, 0
	s_min_u32 s1, s0, 32
	s_lshl_b32 s0, s0, 4
	s_add_i32 s0, s0, s1
	s_lshl_b32 s69, s0, 4
	v_readfirstlane_b32 s70, v4
	v_and_b32_e32 v6, 15, v5
	v_lshrrev_b32_e32 v7, 4, v5
	s_waitcnt lgkmcnt(0)
	v_readfirstlane_b32 s66, v2
	v_readfirstlane_b32 s67, v3
	s_lshl_b32 s62, s70, 10
	v_and_b32_e32 v8, 7, v6
	v_xor_b32_e32 v9, v7, v8
	v_lshlrev_b32_e32 v9, 4, v9
	v_lshl_add_u32 v156, v6, 7, v9
	v_add_u32_e32 v10, 4, v7
	v_xor_b32_e32 v10, v10, v8
	v_lshlrev_b32_e32 v10, 4, v10
	v_lshl_add_u32 v157, v6, 7, v10
	v_add_u32_e32 v158, 0x8800, v156
	v_add_u32_e32 v159, 0x8800, v157
	v_lshl_add_u32 v11, v4, 5, v6
	s_mov_b32 s2, 0x2000
	v_mul_lo_u32 v11, v11, s2
	v_lshl_add_u32 v160, v7, 4, v11
	v_add_u32_e32 v161, 0x20000, v160
	v_lshrrev_b32_e32 v11, 3, v163
	v_and_b32_e32 v12, 7, v163
	v_and_b32_e32 v13, 7, v11
	v_xor_b32_e32 v12, v12, v13
	v_lshlrev_b32_e32 v12, 4, v12
	s_mov_b32 s2, 0x2000
	v_mul_lo_u32 v11, v11, s2
	v_add_u32_e32 v162, v11, v12
	v_lshrrev_b32_e32 v11, 1, v7
	v_lshl_add_u32 v11, v4, 2, v11
	v_xor_b32_e32 v12, v11, v6
	v_lshlrev_b32_e32 v12, 4, v12
	v_and_b32_e32 v13, 1, v7
	v_lshlrev_b32_e32 v13, 3, v13
	v_lshl_add_u32 v14, v6, 8, v13
	v_add_u32_e32 v212, v14, v12
	v_add_u32_e32 v11, 2, v11
	v_xor_b32_e32 v12, v11, v6
	v_lshlrev_b32_e32 v12, 4, v12
	v_add_u32_e32 v213, v14, v12
	v_lshrrev_b32_e32 v11, 4, v163
	v_and_b32_e32 v12, 15, v163
	v_xor_b32_e32 v13, v12, v11
	v_lshlrev_b32_e32 v13, 4, v13
	v_lshl_add_u32 v247, v11, 8, v13
	s_mov_b32 s2, 0x800
	v_mul_lo_u32 v11, v11, s2
	v_lshl_add_u32 v252, v12, 4, v11
	s_mov_b32 s64, 0
.Lg2_ff2_tile:
	s_lshl_b32 s0, s64, 3
	s_add_i32 s0, s0, s68
	s_lshl_b32 s0, s0, 7
	s_mul_i32 s2, s69, 0x2000
	s_mul_hi_u32 s3, s69, 0x2000
	s_add_u32 s56, s26, s2
	s_addc_u32 s57, s27, s3
	s_add_u32 s56, s56, 0x0
	s_addc_u32 s57, s57, 0
	s_mul_i32 s2, s0, 0x2000
	s_mul_hi_u32 s3, s0, 0x2000
	s_add_u32 s58, s26, s2
	s_addc_u32 s59, s27, s3
	s_add_u32 s58, s58, 0x10740000
	s_addc_u32 s59, s59, 0
	s_mul_i32 s2, s69, 0x800
	s_mul_hi_u32 s3, s69, 0x800
	s_lshl_b32 s0, s0, 1
	s_add_u32 s2, s2, s0
	s_addc_u32 s3, s3, 0
	s_add_u32 s60, s26, s2
	s_addc_u32 s61, s27, s3
	s_add_u32 s60, s60, 0x11140000
	s_addc_u32 s61, s61, 0
	v_mov_b32_e32 v0, 0
	v_mov_b32_e32 v1, 0
	v_mov_b32_e32 v2, 0
	v_mov_b32_e32 v3, 0
	v_mov_b32_e32 v4, 0
	v_mov_b32_e32 v5, 0
	v_mov_b32_e32 v6, 0
	v_mov_b32_e32 v7, 0
	v_mov_b32_e32 v8, 0
	v_mov_b32_e32 v9, 0
	v_mov_b32_e32 v10, 0
	v_mov_b32_e32 v11, 0
	v_mov_b32_e32 v12, 0
	v_mov_b32_e32 v13, 0
	v_mov_b32_e32 v14, 0
	v_mov_b32_e32 v15, 0
	v_mov_b32_e32 v16, 0
	v_mov_b32_e32 v17, 0
	v_mov_b32_e32 v18, 0
	v_mov_b32_e32 v19, 0
	v_mov_b32_e32 v20, 0
	v_mov_b32_e32 v21, 0
	v_mov_b32_e32 v22, 0
	v_mov_b32_e32 v23, 0
	v_mov_b32_e32 v24, 0
	v_mov_b32_e32 v25, 0
	v_mov_b32_e32 v26, 0
	v_mov_b32_e32 v27, 0
	v_mov_b32_e32 v28, 0
	v_mov_b32_e32 v29, 0
	v_mov_b32_e32 v30, 0
	v_mov_b32_e32 v31, 0
	v_mov_b32_e32 v32, 0
	v_mov_b32_e32 v33, 0
	v_mov_b32_e32 v34, 0
	v_mov_b32_e32 v35, 0
	v_mov_b32_e32 v36, 0
	v_mov_b32_e32 v37, 0
	v_mov_b32_e32 v38, 0
	v_mov_b32_e32 v39, 0
	v_mov_b32_e32 v40, 0
	v_mov_b32_e32 v41, 0
	v_mov_b32_e32 v42, 0
	v_mov_b32_e32 v43, 0
	v_mov_b32_e32 v44, 0
	v_mov_b32_e32 v45, 0
	v_mov_b32_e32 v46, 0
	v_mov_b32_e32 v47, 0
	v_mov_b32_e32 v48, 0
	v_mov_b32_e32 v49, 0
	v_mov_b32_e32 v50, 0
	v_mov_b32_e32 v51, 0
	v_mov_b32_e32 v52, 0
	v_mov_b32_e32 v53, 0
	v_mov_b32_e32 v54, 0
	v_mov_b32_e32 v55, 0
	v_mov_b32_e32 v56, 0
	v_mov_b32_e32 v57, 0
	v_mov_b32_e32 v58, 0
	v_mov_b32_e32 v59, 0
	v_mov_b32_e32 v60, 0
	v_mov_b32_e32 v61, 0
	v_mov_b32_e32 v62, 0
	v_mov_b32_e32 v63, 0
	v_mov_b32_e32 v64, 0
	v_mov_b32_e32 v65, 0
	v_mov_b32_e32 v66, 0
	v_mov_b32_e32 v67, 0
	v_mov_b32_e32 v68, 0
	v_mov_b32_e32 v69, 0
	v_mov_b32_e32 v70, 0
	v_mov_b32_e32 v71, 0
	v_mov_b32_e32 v72, 0
	v_mov_b32_e32 v73, 0
	v_mov_b32_e32 v74, 0
	v_mov_b32_e32 v75, 0
	v_mov_b32_e32 v76, 0
	v_mov_b32_e32 v77, 0
	v_mov_b32_e32 v78, 0
	v_mov_b32_e32 v79, 0
	v_mov_b32_e32 v80, 0
	v_mov_b32_e32 v81, 0
	v_mov_b32_e32 v82, 0
	v_mov_b32_e32 v83, 0
	v_mov_b32_e32 v84, 0
	v_mov_b32_e32 v85, 0
	v_mov_b32_e32 v86, 0
	v_mov_b32_e32 v87, 0
	v_mov_b32_e32 v88, 0
	v_mov_b32_e32 v89, 0
	v_mov_b32_e32 v90, 0
	v_mov_b32_e32 v91, 0
	v_mov_b32_e32 v92, 0
	v_mov_b32_e32 v93, 0
	v_mov_b32_e32 v94, 0
	v_mov_b32_e32 v95, 0
	v_mov_b32_e32 v96, 0
	v_mov_b32_e32 v97, 0
	v_mov_b32_e32 v98, 0
	v_mov_b32_e32 v99, 0
	v_mov_b32_e32 v100, 0
	v_mov_b32_e32 v101, 0
	v_mov_b32_e32 v102, 0
	v_mov_b32_e32 v103, 0
	v_mov_b32_e32 v104, 0
	v_mov_b32_e32 v105, 0
	v_mov_b32_e32 v106, 0
	v_mov_b32_e32 v107, 0
	v_mov_b32_e32 v108, 0
	v_mov_b32_e32 v109, 0
	v_mov_b32_e32 v110, 0
	v_mov_b32_e32 v111, 0
	v_mov_b32_e32 v112, 0
	v_mov_b32_e32 v113, 0
	v_mov_b32_e32 v114, 0
	v_mov_b32_e32 v115, 0
	v_mov_b32_e32 v116, 0
	v_mov_b32_e32 v117, 0
	v_mov_b32_e32 v118, 0
	v_mov_b32_e32 v119, 0
	v_mov_b32_e32 v120, 0
	v_mov_b32_e32 v121, 0
	v_mov_b32_e32 v122, 0
	v_mov_b32_e32 v123, 0
	v_mov_b32_e32 v124, 0
	v_mov_b32_e32 v125, 0
	v_mov_b32_e32 v126, 0
	v_mov_b32_e32 v127, 0
	v_mov_b32_e32 v128, 0
	v_mov_b32_e32 v129, 0
	v_mov_b32_e32 v130, 0
	v_mov_b32_e32 v131, 0
	v_mov_b32_e32 v132, 0
	v_mov_b32_e32 v133, 0
	v_mov_b32_e32 v134, 0
	v_mov_b32_e32 v135, 0
	s_add_u32 s4, s56, 0x0
	s_addc_u32 s5, s57, 0
	s_add_u32 m0, s62, 0x0
	s_nop 0
	global_load_lds_dwordx4 v162, s[4:5]
	s_add_u32 s4, s56, 0x40000
	s_addc_u32 s5, s57, 0
	s_add_u32 m0, s62, 0x1000
	s_nop 0
	global_load_lds_dwordx4 v162, s[4:5]
	s_add_u32 s4, s56, 0x80000
	s_addc_u32 s5, s57, 0
	s_add_u32 m0, s62, 0x2000
	s_nop 0
	global_load_lds_dwordx4 v162, s[4:5]
	s_add_u32 s4, s56, 0xc0000
	s_addc_u32 s5, s57, 0
	s_add_u32 m0, s62, 0x3000
	s_nop 0
	global_load_lds_dwordx4 v162, s[4:5]
	s_add_u32 s4, s56, 0x100000
	s_addc_u32 s5, s57, 0
	s_add_u32 m0, s62, 0x4000
	s_nop 0
	global_load_lds_dwordx4 v162, s[4:5]
	s_add_u32 s4, s56, 0x140000
	s_addc_u32 s5, s57, 0
	s_add_u32 m0, s62, 0x5000
	s_nop 0
	global_load_lds_dwordx4 v162, s[4:5]
	s_add_u32 s4, s56, 0x180000
	s_addc_u32 s5, s57, 0
	s_add_u32 m0, s62, 0x6000
	s_nop 0
	global_load_lds_dwordx4 v162, s[4:5]
	s_add_u32 s4, s56, 0x1c0000
	s_addc_u32 s5, s57, 0
	s_add_u32 m0, s62, 0x7000
	s_nop 0
	global_load_lds_dwordx4 v162, s[4:5]
	s_cmp_eq_u32 s65, 0
	s_cbranch_scc1 .Lg2_ff2_nodma8_0
	s_cmp_gt_u32 s70, 1
	s_cbranch_scc1 .Lg2_ff2_nodma8_0
	s_add_u32 s4, s56, 0x200000
	s_addc_u32 s5, s57, 0
	s_add_u32 m0, s62, 0x8000
	s_nop 0
	global_load_lds_dwordx4 v162, s[4:5]
.Lg2_ff2_nodma8_0:
	global_load_dwordx4 v[184:187], v160, s[58:59] offset:0
	global_load_dwordx4 v[188:191], v160, s[58:59] offset:64
	global_load_dwordx4 v[192:195], v161, s[58:59] offset:0
	global_load_dwordx4 v[196:199], v161, s[58:59] offset:64
	s_mov_b32 s63, 0
	s_cmp_eq_u32 s65, 0
	s_cbranch_scc1 .Lg2_ff2_loop16
.Lg2_ff2_loop17:
	s_waitcnt vmcnt(0)
	s_barrier
	s_add_u32 s56, s56, 0x80
	s_addc_u32 s57, s57, 0
	s_add_u32 s58, s58, 0x80
	s_addc_u32 s59, s59, 0
	s_add_u32 s4, s56, 0x0
	s_addc_u32 s5, s57, 0
	s_add_u32 m0, s62, 0x8800
	s_nop 0
	global_load_lds_dwordx4 v162, s[4:5]
	s_add_u32 s4, s56, 0x40000
	s_addc_u32 s5, s57, 0
	s_add_u32 m0, s62, 0x9800
	s_nop 0
	global_load_lds_dwordx4 v162, s[4:5]
	s_add_u32 s4, s56, 0x80000
	s_addc_u32 s5, s57, 0
	s_add_u32 m0, s62, 0xa800
	s_nop 0
	global_load_lds_dwordx4 v162, s[4:5]
	s_add_u32 s4, s56, 0xc0000
	s_addc_u32 s5, s57, 0
	s_add_u32 m0, s62, 0xb800
	s_nop 0
	global_load_lds_dwordx4 v162, s[4:5]
	s_add_u32 s4, s56, 0x100000
	s_addc_u32 s5, s57, 0
	s_add_u32 m0, s62, 0xc800
	s_nop 0
	global_load_lds_dwordx4 v162, s[4:5]
	s_add_u32 s4, s56, 0x140000
	s_addc_u32 s5, s57, 0
	s_add_u32 m0, s62, 0xd800
	s_nop 0
	global_load_lds_dwordx4 v162, s[4:5]
	s_add_u32 s4, s56, 0x180000
	s_addc_u32 s5, s57, 0
	s_add_u32 m0, s62, 0xe800
	s_nop 0
	global_load_lds_dwordx4 v162, s[4:5]
	s_add_u32 s4, s56, 0x1c0000
	s_addc_u32 s5, s57, 0
	s_add_u32 m0, s62, 0xf800
	s_nop 0
	global_load_lds_dwordx4 v162, s[4:5]
	s_cmp_eq_u32 s65, 0
	s_cbranch_scc1 .Lg2_ff2_nodma8_1
	s_cmp_gt_u32 s70, 1
	s_cbranch_scc1 .Lg2_ff2_nodma8_1
	s_add_u32 s4, s56, 0x200000
	s_addc_u32 s5, s57, 0
	s_add_u32 m0, s62, 0x10800
	s_nop 0
	global_load_lds_dwordx4 v162, s[4:5]
.Lg2_ff2_nodma8_1:
	global_load_dwordx4 v[200:203], v160, s[58:59] offset:0
	global_load_dwordx4 v[204:207], v160, s[58:59] offset:64
	global_load_dwordx4 v[208:211], v161, s[58:59] offset:0
	global_load_dwordx4 v[240:243], v161, s[58:59] offset:64
	ds_read_b128 v[136:139], v156 offset:0
	ds_read_b128 v[140:143], v156 offset:2048
	ds_read_b128 v[144:147], v156 offset:4096
	ds_read_b128 v[148:151], v156 offset:6144
	ds_read_b128 v[164:167], v156 offset:8192
	ds_read_b128 v[168:171], v156 offset:10240
	ds_read_b128 v[172:175], v156 offset:12288
	ds_read_b128 v[176:179], v156 offset:14336
	s_waitcnt lgkmcnt(4)
	v_mfma_f32_16x16x32_bf16 v[0:3], v[184:187], v[136:139], v[0:3]
	v_mfma_f32_16x16x32_bf16 v[4:7], v[192:195], v[136:139], v[4:7]
	v_mfma_f32_16x16x32_bf16 v[8:11], v[184:187], v[140:143], v[8:11]
	v_mfma_f32_16x16x32_bf16 v[12:15], v[192:195], v[140:143], v[12:15]
	v_mfma_f32_16x16x32_bf16 v[16:19], v[184:187], v[144:147], v[16:19]
	v_mfma_f32_16x16x32_bf16 v[20:23], v[192:195], v[144:147], v[20:23]
	v_mfma_f32_16x16x32_bf16 v[24:27], v[184:187], v[148:151], v[24:27]
	v_mfma_f32_16x16x32_bf16 v[28:31], v[192:195], v[148:151], v[28:31]
	ds_read_b128 v[136:139], v156 offset:16384
	ds_read_b128 v[140:143], v156 offset:18432
	ds_read_b128 v[144:147], v156 offset:20480
	ds_read_b128 v[148:151], v156 offset:22528
	s_waitcnt lgkmcnt(4)
	v_mfma_f32_16x16x32_bf16 v[32:35], v[184:187], v[164:167], v[32:35]
	v_mfma_f32_16x16x32_bf16 v[36:39], v[192:195], v[164:167], v[36:39]
	v_mfma_f32_16x16x32_bf16 v[40:43], v[184:187], v[168:171], v[40:43]
	v_mfma_f32_16x16x32_bf16 v[44:47], v[192:195], v[168:171], v[44:47]
	v_mfma_f32_16x16x32_bf16 v[48:51], v[184:187], v[172:175], v[48:51]
	v_mfma_f32_16x16x32_bf16 v[52:55], v[192:195], v[172:175], v[52:55]
	v_mfma_f32_16x16x32_bf16 v[56:59], v[184:187], v[176:179], v[56:59]
	v_mfma_f32_16x16x32_bf16 v[60:63], v[192:195], v[176:179], v[60:63]
	ds_read_b128 v[164:167], v156 offset:24576
	ds_read_b128 v[168:171], v156 offset:26624
	ds_read_b128 v[172:175], v156 offset:28672
	ds_read_b128 v[176:179], v156 offset:30720
	ds_read_b128 v[180:183], v156 offset:32768
	s_waitcnt lgkmcnt(5)
	v_mfma_f32_16x16x32_bf16 v[64:67], v[184:187], v[136:139], v[64:67]
	v_mfma_f32_16x16x32_bf16 v[68:71], v[192:195], v[136:139], v[68:71]
	v_mfma_f32_16x16x32_bf16 v[72:75], v[184:187], v[140:143], v[72:75]
	v_mfma_f32_16x16x32_bf16 v[76:79], v[192:195], v[140:143], v[76:79]
	v_mfma_f32_16x16x32_bf16 v[80:83], v[184:187], v[144:147], v[80:83]
	v_mfma_f32_16x16x32_bf16 v[84:87], v[192:195], v[144:147], v[84:87]
	v_mfma_f32_16x16x32_bf16 v[88:91], v[184:187], v[148:151], v[88:91]
	v_mfma_f32_16x16x32_bf16 v[92:95], v[192:195], v[148:151], v[92:95]
	ds_read_b128 v[136:139], v157 offset:0
	ds_read_b128 v[140:143], v157 offset:2048
	ds_read_b128 v[144:147], v157 offset:4096
	ds_read_b128 v[148:151], v157 offset:6144
	s_waitcnt lgkmcnt(4)
	v_mfma_f32_16x16x32_bf16 v[96:99], v[184:187], v[164:167], v[96:99]
	v_mfma_f32_16x16x32_bf16 v[100:103], v[192:195], v[164:167], v[100:103]
	v_mfma_f32_16x16x32_bf16 v[104:107], v[184:187], v[168:171], v[104:107]
	v_mfma_f32_16x16x32_bf16 v[108:111], v[192:195], v[168:171], v[108:111]
	v_mfma_f32_16x16x32_bf16 v[112:115], v[184:187], v[172:175], v[112:115]
	v_mfma_f32_16x16x32_bf16 v[116:119], v[192:195], v[172:175], v[116:119]
	v_mfma_f32_16x16x32_bf16 v[120:123], v[184:187], v[176:179], v[120:123]
	v_mfma_f32_16x16x32_bf16 v[124:127], v[192:195], v[176:179], v[124:127]
	v_mfma_f32_16x16x32_bf16 v[128:131], v[184:187], v[180:183], v[128:131]
	v_mfma_f32_16x16x32_bf16 v[132:135], v[192:195], v[180:183], v[132:135]
	ds_read_b128 v[164:167], v157 offset:8192
	ds_read_b128 v[168:171], v157 offset:10240
	ds_read_b128 v[172:175], v157 offset:12288
	ds_read_b128 v[176:179], v157 offset:14336
	s_waitcnt lgkmcnt(4)
	v_mfma_f32_16x16x32_bf16 v[0:3], v[188:191], v[136:139], v[0:3]
	v_mfma_f32_16x16x32_bf16 v[4:7], v[196:199], v[136:139], v[4:7]
	v_mfma_f32_16x16x32_bf16 v[8:11], v[188:191], v[140:143], v[8:11]
	v_mfma_f32_16x16x32_bf16 v[12:15], v[196:199], v[140:143], v[12:15]
	v_mfma_f32_16x16x32_bf16 v[16:19], v[188:191], v[144:147], v[16:19]
	v_mfma_f32_16x16x32_bf16 v[20:23], v[196:199], v[144:147], v[20:23]
	v_mfma_f32_16x16x32_bf16 v[24:27], v[188:191], v[148:151], v[24:27]
	v_mfma_f32_16x16x32_bf16 v[28:31], v[196:199], v[148:151], v[28:31]
	ds_read_b128 v[136:139], v157 offset:16384
	ds_read_b128 v[140:143], v157 offset:18432
	ds_read_b128 v[144:147], v157 offset:20480
	ds_read_b128 v[148:151], v157 offset:22528
	s_waitcnt lgkmcnt(4)
	v_mfma_f32_16x16x32_bf16 v[32:35], v[188:191], v[164:167], v[32:35]
	v_mfma_f32_16x16x32_bf16 v[36:39], v[196:199], v[164:167], v[36:39]
	v_mfma_f32_16x16x32_bf16 v[40:43], v[188:191], v[168:171], v[40:43]
	v_mfma_f32_16x16x32_bf16 v[44:47], v[196:199], v[168:171], v[44:47]
	v_mfma_f32_16x16x32_bf16 v[48:51], v[188:191], v[172:175], v[48:51]
	v_mfma_f32_16x16x32_bf16 v[52:55], v[196:199], v[172:175], v[52:55]
	v_mfma_f32_16x16x32_bf16 v[56:59], v[188:191], v[176:179], v[56:59]
	v_mfma_f32_16x16x32_bf16 v[60:63], v[196:199], v[176:179], v[60:63]
	ds_read_b128 v[164:167], v157 offset:24576
	ds_read_b128 v[168:171], v157 offset:26624
	ds_read_b128 v[172:175], v157 offset:28672
	ds_read_b128 v[176:179], v157 offset:30720
	ds_read_b128 v[180:183], v157 offset:32768
	s_waitcnt lgkmcnt(5)
	v_mfma_f32_16x16x32_bf16 v[64:67], v[188:191], v[136:139], v[64:67]
	v_mfma_f32_16x16x32_bf16 v[68:71], v[196:199], v[136:139], v[68:71]
	v_mfma_f32_16x16x32_bf16 v[72:75], v[188:191], v[140:143], v[72:75]
	v_mfma_f32_16x16x32_bf16 v[76:79], v[196:199], v[140:143], v[76:79]
	v_mfma_f32_16x16x32_bf16 v[80:83], v[188:191], v[144:147], v[80:83]
	v_mfma_f32_16x16x32_bf16 v[84:87], v[196:199], v[144:147], v[84:87]
	v_mfma_f32_16x16x32_bf16 v[88:91], v[188:191], v[148:151], v[88:91]
	v_mfma_f32_16x16x32_bf16 v[92:95], v[196:199], v[148:151], v[92:95]
	s_waitcnt lgkmcnt(0)
	v_mfma_f32_16x16x32_bf16 v[96:99], v[188:191], v[164:167], v[96:99]
	v_mfma_f32_16x16x32_bf16 v[100:103], v[196:199], v[164:167], v[100:103]
	v_mfma_f32_16x16x32_bf16 v[104:107], v[188:191], v[168:171], v[104:107]
	v_mfma_f32_16x16x32_bf16 v[108:111], v[196:199], v[168:171], v[108:111]
	v_mfma_f32_16x16x32_bf16 v[112:115], v[188:191], v[172:175], v[112:115]
	v_mfma_f32_16x16x32_bf16 v[116:119], v[196:199], v[172:175], v[116:119]
	v_mfma_f32_16x16x32_bf16 v[120:123], v[188:191], v[176:179], v[120:123]
	v_mfma_f32_16x16x32_bf16 v[124:127], v[196:199], v[176:179], v[124:127]
	v_mfma_f32_16x16x32_bf16 v[128:131], v[188:191], v[180:183], v[128:131]
	v_mfma_f32_16x16x32_bf16 v[132:135], v[196:199], v[180:183], v[132:135]
	s_waitcnt vmcnt(0)
	s_barrier
	s_cmp_ge_u32 s63, 62
	s_cbranch_scc1 .Lg2_ff2_noissue17
	s_add_u32 s56, s56, 0x80
	s_addc_u32 s57, s57, 0
	s_add_u32 s58, s58, 0x80
	s_addc_u32 s59, s59, 0
	s_add_u32 s4, s56, 0x0
	s_addc_u32 s5, s57, 0
	s_add_u32 m0, s62, 0x0
	s_nop 0
	global_load_lds_dwordx4 v162, s[4:5]
	s_add_u32 s4, s56, 0x40000
	s_addc_u32 s5, s57, 0
	s_add_u32 m0, s62, 0x1000
	s_nop 0
	global_load_lds_dwordx4 v162, s[4:5]
	s_add_u32 s4, s56, 0x80000
	s_addc_u32 s5, s57, 0
	s_add_u32 m0, s62, 0x2000
	s_nop 0
	global_load_lds_dwordx4 v162, s[4:5]
	s_add_u32 s4, s56, 0xc0000
	s_addc_u32 s5, s57, 0
	s_add_u32 m0, s62, 0x3000
	s_nop 0
	global_load_lds_dwordx4 v162, s[4:5]
	s_add_u32 s4, s56, 0x100000
	s_addc_u32 s5, s57, 0
	s_add_u32 m0, s62, 0x4000
	s_nop 0
	global_load_lds_dwordx4 v162, s[4:5]
	s_add_u32 s4, s56, 0x140000
	s_addc_u32 s5, s57, 0
	s_add_u32 m0, s62, 0x5000
	s_nop 0
	global_load_lds_dwordx4 v162, s[4:5]
	s_add_u32 s4, s56, 0x180000
	s_addc_u32 s5, s57, 0
	s_add_u32 m0, s62, 0x6000
	s_nop 0
	global_load_lds_dwordx4 v162, s[4:5]
	s_add_u32 s4, s56, 0x1c0000
	s_addc_u32 s5, s57, 0
	s_add_u32 m0, s62, 0x7000
	s_nop 0
	global_load_lds_dwordx4 v162, s[4:5]
	s_cmp_eq_u32 s65, 0
	s_cbranch_scc1 .Lg2_ff2_nodma8_2
	s_cmp_gt_u32 s70, 1
	s_cbranch_scc1 .Lg2_ff2_nodma8_2
	s_add_u32 s4, s56, 0x200000
	s_addc_u32 s5, s57, 0
	s_add_u32 m0, s62, 0x8000
	s_nop 0
	global_load_lds_dwordx4 v162, s[4:5]
.Lg2_ff2_nodma8_2:
	global_load_dwordx4 v[184:187], v160, s[58:59] offset:0
	global_load_dwordx4 v[188:191], v160, s[58:59] offset:64
	global_load_dwordx4 v[192:195], v161, s[58:59] offset:0
	global_load_dwordx4 v[196:199], v161, s[58:59] offset:64
.Lg2_ff2_noissue17:
	ds_read_b128 v[136:139], v158 offset:0
	ds_read_b128 v[140:143], v158 offset:2048
	ds_read_b128 v[144:147], v158 offset:4096
	ds_read_b128 v[148:151], v158 offset:6144
	ds_read_b128 v[164:167], v158 offset:8192
	ds_read_b128 v[168:171], v158 offset:10240
	ds_read_b128 v[172:175], v158 offset:12288
	ds_read_b128 v[176:179], v158 offset:14336
	s_waitcnt lgkmcnt(4)
	v_mfma_f32_16x16x32_bf16 v[0:3], v[200:203], v[136:139], v[0:3]
	v_mfma_f32_16x16x32_bf16 v[4:7], v[208:211], v[136:139], v[4:7]
	v_mfma_f32_16x16x32_bf16 v[8:11], v[200:203], v[140:143], v[8:11]
	v_mfma_f32_16x16x32_bf16 v[12:15], v[208:211], v[140:143], v[12:15]
	v_mfma_f32_16x16x32_bf16 v[16:19], v[200:203], v[144:147], v[16:19]
	v_mfma_f32_16x16x32_bf16 v[20:23], v[208:211], v[144:147], v[20:23]
	v_mfma_f32_16x16x32_bf16 v[24:27], v[200:203], v[148:151], v[24:27]
	v_mfma_f32_16x16x32_bf16 v[28:31], v[208:211], v[148:151], v[28:31]
	ds_read_b128 v[136:139], v158 offset:16384
	ds_read_b128 v[140:143], v158 offset:18432
	ds_read_b128 v[144:147], v158 offset:20480
	ds_read_b128 v[148:151], v158 offset:22528
	s_waitcnt lgkmcnt(4)
	v_mfma_f32_16x16x32_bf16 v[32:35], v[200:203], v[164:167], v[32:35]
	v_mfma_f32_16x16x32_bf16 v[36:39], v[208:211], v[164:167], v[36:39]
	v_mfma_f32_16x16x32_bf16 v[40:43], v[200:203], v[168:171], v[40:43]
	v_mfma_f32_16x16x32_bf16 v[44:47], v[208:211], v[168:171], v[44:47]
	v_mfma_f32_16x16x32_bf16 v[48:51], v[200:203], v[172:175], v[48:51]
	v_mfma_f32_16x16x32_bf16 v[52:55], v[208:211], v[172:175], v[52:55]
	v_mfma_f32_16x16x32_bf16 v[56:59], v[200:203], v[176:179], v[56:59]
	v_mfma_f32_16x16x32_bf16 v[60:63], v[208:211], v[176:179], v[60:63]
	ds_read_b128 v[164:167], v158 offset:24576
	ds_read_b128 v[168:171], v158 offset:26624
	ds_read_b128 v[172:175], v158 offset:28672
	ds_read_b128 v[176:179], v158 offset:30720
	ds_read_b128 v[180:183], v158 offset:32768
	s_waitcnt lgkmcnt(5)
	v_mfma_f32_16x16x32_bf16 v[64:67], v[200:203], v[136:139], v[64:67]
	v_mfma_f32_16x16x32_bf16 v[68:71], v[208:211], v[136:139], v[68:71]
	v_mfma_f32_16x16x32_bf16 v[72:75], v[200:203], v[140:143], v[72:75]
	v_mfma_f32_16x16x32_bf16 v[76:79], v[208:211], v[140:143], v[76:79]
	v_mfma_f32_16x16x32_bf16 v[80:83], v[200:203], v[144:147], v[80:83]
	v_mfma_f32_16x16x32_bf16 v[84:87], v[208:211], v[144:147], v[84:87]
	v_mfma_f32_16x16x32_bf16 v[88:91], v[200:203], v[148:151], v[88:91]
	v_mfma_f32_16x16x32_bf16 v[92:95], v[208:211], v[148:151], v[92:95]
	ds_read_b128 v[136:139], v159 offset:0
	ds_read_b128 v[140:143], v159 offset:2048
	ds_read_b128 v[144:147], v159 offset:4096
	ds_read_b128 v[148:151], v159 offset:6144
	s_waitcnt lgkmcnt(4)
	v_mfma_f32_16x16x32_bf16 v[96:99], v[200:203], v[164:167], v[96:99]
	v_mfma_f32_16x16x32_bf16 v[100:103], v[208:211], v[164:167], v[100:103]
	v_mfma_f32_16x16x32_bf16 v[104:107], v[200:203], v[168:171], v[104:107]
	v_mfma_f32_16x16x32_bf16 v[108:111], v[208:211], v[168:171], v[108:111]
	v_mfma_f32_16x16x32_bf16 v[112:115], v[200:203], v[172:175], v[112:115]
	v_mfma_f32_16x16x32_bf16 v[116:119], v[208:211], v[172:175], v[116:119]
	v_mfma_f32_16x16x32_bf16 v[120:123], v[200:203], v[176:179], v[120:123]
	v_mfma_f32_16x16x32_bf16 v[124:127], v[208:211], v[176:179], v[124:127]
	v_mfma_f32_16x16x32_bf16 v[128:131], v[200:203], v[180:183], v[128:131]
	v_mfma_f32_16x16x32_bf16 v[132:135], v[208:211], v[180:183], v[132:135]
	ds_read_b128 v[164:167], v159 offset:8192
	ds_read_b128 v[168:171], v159 offset:10240
	ds_read_b128 v[172:175], v159 offset:12288
	ds_read_b128 v[176:179], v159 offset:14336
	s_waitcnt lgkmcnt(4)
	v_mfma_f32_16x16x32_bf16 v[0:3], v[204:207], v[136:139], v[0:3]
	v_mfma_f32_16x16x32_bf16 v[4:7], v[240:243], v[136:139], v[4:7]
	v_mfma_f32_16x16x32_bf16 v[8:11], v[204:207], v[140:143], v[8:11]
	v_mfma_f32_16x16x32_bf16 v[12:15], v[240:243], v[140:143], v[12:15]
	v_mfma_f32_16x16x32_bf16 v[16:19], v[204:207], v[144:147], v[16:19]
	v_mfma_f32_16x16x32_bf16 v[20:23], v[240:243], v[144:147], v[20:23]
	v_mfma_f32_16x16x32_bf16 v[24:27], v[204:207], v[148:151], v[24:27]
	v_mfma_f32_16x16x32_bf16 v[28:31], v[240:243], v[148:151], v[28:31]
	ds_read_b128 v[136:139], v159 offset:16384
	ds_read_b128 v[140:143], v159 offset:18432
	ds_read_b128 v[144:147], v159 offset:20480
	ds_read_b128 v[148:151], v159 offset:22528
	s_waitcnt lgkmcnt(4)
	v_mfma_f32_16x16x32_bf16 v[32:35], v[204:207], v[164:167], v[32:35]
	v_mfma_f32_16x16x32_bf16 v[36:39], v[240:243], v[164:167], v[36:39]
	v_mfma_f32_16x16x32_bf16 v[40:43], v[204:207], v[168:171], v[40:43]
	v_mfma_f32_16x16x32_bf16 v[44:47], v[240:243], v[168:171], v[44:47]
	v_mfma_f32_16x16x32_bf16 v[48:51], v[204:207], v[172:175], v[48:51]
	v_mfma_f32_16x16x32_bf16 v[52:55], v[240:243], v[172:175], v[52:55]
	v_mfma_f32_16x16x32_bf16 v[56:59], v[204:207], v[176:179], v[56:59]
	v_mfma_f32_16x16x32_bf16 v[60:63], v[240:243], v[176:179], v[60:63]
	ds_read_b128 v[164:167], v159 offset:24576
	ds_read_b128 v[168:171], v159 offset:26624
	ds_read_b128 v[172:175], v159 offset:28672
	ds_read_b128 v[176:179], v159 offset:30720
	ds_read_b128 v[180:183], v159 offset:32768
	s_waitcnt lgkmcnt(5)
	v_mfma_f32_16x16x32_bf16 v[64:67], v[204:207], v[136:139], v[64:67]
	v_mfma_f32_16x16x32_bf16 v[68:71], v[240:243], v[136:139], v[68:71]
	v_mfma_f32_16x16x32_bf16 v[72:75], v[204:207], v[140:143], v[72:75]
	v_mfma_f32_16x16x32_bf16 v[76:79], v[240:243], v[140:143], v[76:79]
	v_mfma_f32_16x16x32_bf16 v[80:83], v[204:207], v[144:147], v[80:83]
	v_mfma_f32_16x16x32_bf16 v[84:87], v[240:243], v[144:147], v[84:87]
	v_mfma_f32_16x16x32_bf16 v[88:91], v[204:207], v[148:151], v[88:91]
	v_mfma_f32_16x16x32_bf16 v[92:95], v[240:243], v[148:151], v[92:95]
	s_waitcnt lgkmcnt(0)
	v_mfma_f32_16x16x32_bf16 v[96:99], v[204:207], v[164:167], v[96:99]
	v_mfma_f32_16x16x32_bf16 v[100:103], v[240:243], v[164:167], v[100:103]
	v_mfma_f32_16x16x32_bf16 v[104:107], v[204:207], v[168:171], v[104:107]
	v_mfma_f32_16x16x32_bf16 v[108:111], v[240:243], v[168:171], v[108:111]
	v_mfma_f32_16x16x32_bf16 v[112:115], v[204:207], v[172:175], v[112:115]
	v_mfma_f32_16x16x32_bf16 v[116:119], v[240:243], v[172:175], v[116:119]
	v_mfma_f32_16x16x32_bf16 v[120:123], v[204:207], v[176:179], v[120:123]
	v_mfma_f32_16x16x32_bf16 v[124:127], v[240:243], v[176:179], v[124:127]
	v_mfma_f32_16x16x32_bf16 v[128:131], v[204:207], v[180:183], v[128:131]
	v_mfma_f32_16x16x32_bf16 v[132:135], v[240:243], v[180:183], v[132:135]
	s_add_i32 s63, s63, 2
	s_cmp_lt_u32 s63, 64
	s_cbranch_scc1 .Lg2_ff2_loop17
	s_branch .Lg2_ff2_epi

.Lg2_ff2_nodma8_3:
	global_load_dwordx4 v[200:203], v160, s[58:59] offset:0
	global_load_dwordx4 v[204:207], v160, s[58:59] offset:64
	global_load_dwordx4 v[208:211], v161, s[58:59] offset:0
	global_load_dwordx4 v[240:243], v161, s[58:59] offset:64
	ds_read_b128 v[136:139], v156 offset:0
	ds_read_b128 v[140:143], v156 offset:2048
	ds_read_b128 v[144:147], v156 offset:4096
	ds_read_b128 v[148:151], v156 offset:6144
	ds_read_b128 v[164:167], v156 offset:8192
	ds_read_b128 v[168:171], v156 offset:10240
	ds_read_b128 v[172:175], v156 offset:12288
	ds_read_b128 v[176:179], v156 offset:14336
	s_waitcnt lgkmcnt(4)
	v_mfma_f32_16x16x32_bf16 v[0:3], v[184:187], v[136:139], v[0:3]
	v_mfma_f32_16x16x32_bf16 v[4:7], v[192:195], v[136:139], v[4:7]
	v_mfma_f32_16x16x32_bf16 v[8:11], v[184:187], v[140:143], v[8:11]
	v_mfma_f32_16x16x32_bf16 v[12:15], v[192:195], v[140:143], v[12:15]
	v_mfma_f32_16x16x32_bf16 v[16:19], v[184:187], v[144:147], v[16:19]
	v_mfma_f32_16x16x32_bf16 v[20:23], v[192:195], v[144:147], v[20:23]
	v_mfma_f32_16x16x32_bf16 v[24:27], v[184:187], v[148:151], v[24:27]
	v_mfma_f32_16x16x32_bf16 v[28:31], v[192:195], v[148:151], v[28:31]
	ds_read_b128 v[136:139], v156 offset:16384
	ds_read_b128 v[140:143], v156 offset:18432
	ds_read_b128 v[144:147], v156 offset:20480
	ds_read_b128 v[148:151], v156 offset:22528
	s_waitcnt lgkmcnt(4)
	v_mfma_f32_16x16x32_bf16 v[32:35], v[184:187], v[164:167], v[32:35]
	v_mfma_f32_16x16x32_bf16 v[36:39], v[192:195], v[164:167], v[36:39]
	v_mfma_f32_16x16x32_bf16 v[40:43], v[184:187], v[168:171], v[40:43]
	v_mfma_f32_16x16x32_bf16 v[44:47], v[192:195], v[168:171], v[44:47]
	v_mfma_f32_16x16x32_bf16 v[48:51], v[184:187], v[172:175], v[48:51]
	v_mfma_f32_16x16x32_bf16 v[52:55], v[192:195], v[172:175], v[52:55]
	v_mfma_f32_16x16x32_bf16 v[56:59], v[184:187], v[176:179], v[56:59]
	v_mfma_f32_16x16x32_bf16 v[60:63], v[192:195], v[176:179], v[60:63]
	ds_read_b128 v[164:167], v156 offset:24576
	ds_read_b128 v[168:171], v156 offset:26624
	ds_read_b128 v[172:175], v156 offset:28672
	ds_read_b128 v[176:179], v156 offset:30720
	s_waitcnt lgkmcnt(4)
	v_mfma_f32_16x16x32_bf16 v[64:67], v[184:187], v[136:139], v[64:67]
	v_mfma_f32_16x16x32_bf16 v[68:71], v[192:195], v[136:139], v[68:71]
	v_mfma_f32_16x16x32_bf16 v[72:75], v[184:187], v[140:143], v[72:75]
	v_mfma_f32_16x16x32_bf16 v[76:79], v[192:195], v[140:143], v[76:79]
	v_mfma_f32_16x16x32_bf16 v[80:83], v[184:187], v[144:147], v[80:83]
	v_mfma_f32_16x16x32_bf16 v[84:87], v[192:195], v[144:147], v[84:87]
	v_mfma_f32_16x16x32_bf16 v[88:91], v[184:187], v[148:151], v[88:91]
	v_mfma_f32_16x16x32_bf16 v[92:95], v[192:195], v[148:151], v[92:95]
	ds_read_b128 v[136:139], v157 offset:0
	ds_read_b128 v[140:143], v157 offset:2048
	ds_read_b128 v[144:147], v157 offset:4096
	ds_read_b128 v[148:151], v157 offset:6144
	s_waitcnt lgkmcnt(4)
	v_mfma_f32_16x16x32_bf16 v[96:99], v[184:187], v[164:167], v[96:99]
	v_mfma_f32_16x16x32_bf16 v[100:103], v[192:195], v[164:167], v[100:103]
	v_mfma_f32_16x16x32_bf16 v[104:107], v[184:187], v[168:171], v[104:107]
	v_mfma_f32_16x16x32_bf16 v[108:111], v[192:195], v[168:171], v[108:111]
	v_mfma_f32_16x16x32_bf16 v[112:115], v[184:187], v[172:175], v[112:115]
	v_mfma_f32_16x16x32_bf16 v[116:119], v[192:195], v[172:175], v[116:119]
	v_mfma_f32_16x16x32_bf16 v[120:123], v[184:187], v[176:179], v[120:123]
	v_mfma_f32_16x16x32_bf16 v[124:127], v[192:195], v[176:179], v[124:127]
	ds_read_b128 v[164:167], v157 offset:8192
	ds_read_b128 v[168:171], v157 offset:10240
	ds_read_b128 v[172:175], v157 offset:12288
	ds_read_b128 v[176:179], v157 offset:14336
	s_waitcnt lgkmcnt(4)
	v_mfma_f32_16x16x32_bf16 v[0:3], v[188:191], v[136:139], v[0:3]
	v_mfma_f32_16x16x32_bf16 v[4:7], v[196:199], v[136:139], v[4:7]
	v_mfma_f32_16x16x32_bf16 v[8:11], v[188:191], v[140:143], v[8:11]
	v_mfma_f32_16x16x32_bf16 v[12:15], v[196:199], v[140:143], v[12:15]
	v_mfma_f32_16x16x32_bf16 v[16:19], v[188:191], v[144:147], v[16:19]
	v_mfma_f32_16x16x32_bf16 v[20:23], v[196:199], v[144:147], v[20:23]
	v_mfma_f32_16x16x32_bf16 v[24:27], v[188:191], v[148:151], v[24:27]
	v_mfma_f32_16x16x32_bf16 v[28:31], v[196:199], v[148:151], v[28:31]
	ds_read_b128 v[136:139], v157 offset:16384
	ds_read_b128 v[140:143], v157 offset:18432
	ds_read_b128 v[144:147], v157 offset:20480
	ds_read_b128 v[148:151], v157 offset:22528
	s_waitcnt lgkmcnt(4)
	v_mfma_f32_16x16x32_bf16 v[32:35], v[188:191], v[164:167], v[32:35]
	v_mfma_f32_16x16x32_bf16 v[36:39], v[196:199], v[164:167], v[36:39]
	v_mfma_f32_16x16x32_bf16 v[40:43], v[188:191], v[168:171], v[40:43]
	v_mfma_f32_16x16x32_bf16 v[44:47], v[196:199], v[168:171], v[44:47]
	v_mfma_f32_16x16x32_bf16 v[48:51], v[188:191], v[172:175], v[48:51]
	v_mfma_f32_16x16x32_bf16 v[52:55], v[196:199], v[172:175], v[52:55]
	v_mfma_f32_16x16x32_bf16 v[56:59], v[188:191], v[176:179], v[56:59]
	v_mfma_f32_16x16x32_bf16 v[60:63], v[196:199], v[176:179], v[60:63]
	ds_read_b128 v[164:167], v157 offset:24576
	ds_read_b128 v[168:171], v157 offset:26624
	ds_read_b128 v[172:175], v157 offset:28672
	ds_read_b128 v[176:179], v157 offset:30720
	s_waitcnt lgkmcnt(4)
	v_mfma_f32_16x16x32_bf16 v[64:67], v[188:191], v[136:139], v[64:67]
	v_mfma_f32_16x16x32_bf16 v[68:71], v[196:199], v[136:139], v[68:71]
	v_mfma_f32_16x16x32_bf16 v[72:75], v[188:191], v[140:143], v[72:75]
	v_mfma_f32_16x16x32_bf16 v[76:79], v[196:199], v[140:143], v[76:79]
	v_mfma_f32_16x16x32_bf16 v[80:83], v[188:191], v[144:147], v[80:83]
	v_mfma_f32_16x16x32_bf16 v[84:87], v[196:199], v[144:147], v[84:87]
	v_mfma_f32_16x16x32_bf16 v[88:91], v[188:191], v[148:151], v[88:91]
	v_mfma_f32_16x16x32_bf16 v[92:95], v[196:199], v[148:151], v[92:95]
	s_waitcnt lgkmcnt(0)
	v_mfma_f32_16x16x32_bf16 v[96:99], v[188:191], v[164:167], v[96:99]
	v_mfma_f32_16x16x32_bf16 v[100:103], v[196:199], v[164:167], v[100:103]
	v_mfma_f32_16x16x32_bf16 v[104:107], v[188:191], v[168:171], v[104:107]
	v_mfma_f32_16x16x32_bf16 v[108:111], v[196:199], v[168:171], v[108:111]
	v_mfma_f32_16x16x32_bf16 v[112:115], v[188:191], v[172:175], v[112:115]
	v_mfma_f32_16x16x32_bf16 v[116:119], v[196:199], v[172:175], v[116:119]
	v_mfma_f32_16x16x32_bf16 v[120:123], v[188:191], v[176:179], v[120:123]
	v_mfma_f32_16x16x32_bf16 v[124:127], v[196:199], v[176:179], v[124:127]
	s_waitcnt vmcnt(0)
	s_barrier
	s_cmp_ge_u32 s63, 62
	s_cbranch_scc1 .Lg2_ff2_noissue16
	s_add_u32 s56, s56, 0x80
	s_addc_u32 s57, s57, 0
	s_add_u32 s58, s58, 0x80
	s_addc_u32 s59, s59, 0
	s_add_u32 s4, s56, 0x0
	s_addc_u32 s5, s57, 0
	s_add_u32 m0, s62, 0x0
	s_nop 0
	global_load_lds_dwordx4 v162, s[4:5]
	s_add_u32 s4, s56, 0x40000
	s_addc_u32 s5, s57, 0
	s_add_u32 m0, s62, 0x1000
	s_nop 0
	global_load_lds_dwordx4 v162, s[4:5]
	s_add_u32 s4, s56, 0x80000
	s_addc_u32 s5, s57, 0
	s_add_u32 m0, s62, 0x2000
	s_nop 0
	global_load_lds_dwordx4 v162, s[4:5]
	s_add_u32 s4, s56, 0xc0000
	s_addc_u32 s5, s57, 0
	s_add_u32 m0, s62, 0x3000
	s_nop 0
	global_load_lds_dwordx4 v162, s[4:5]
	s_add_u32 s4, s56, 0x100000
	s_addc_u32 s5, s57, 0
	s_add_u32 m0, s62, 0x4000
	s_nop 0
	global_load_lds_dwordx4 v162, s[4:5]
	s_add_u32 s4, s56, 0x140000
	s_addc_u32 s5, s57, 0
	s_add_u32 m0, s62, 0x5000
	s_nop 0
	global_load_lds_dwordx4 v162, s[4:5]
	s_add_u32 s4, s56, 0x180000
	s_addc_u32 s5, s57, 0
	s_add_u32 m0, s62, 0x6000
	s_nop 0
	global_load_lds_dwordx4 v162, s[4:5]
	s_add_u32 s4, s56, 0x1c0000
	s_addc_u32 s5, s57, 0
	s_add_u32 m0, s62, 0x7000
	s_nop 0
	global_load_lds_dwordx4 v162, s[4:5]
	s_cmp_eq_u32 s65, 0
	s_cbranch_scc1 .Lg2_ff2_nodma8_4
	s_cmp_gt_u32 s70, 1
	s_cbranch_scc1 .Lg2_ff2_nodma8_4
	s_add_u32 s4, s56, 0x200000
	s_addc_u32 s5, s57, 0
	s_add_u32 m0, s62, 0x8000
	s_nop 0
	global_load_lds_dwordx4 v162, s[4:5]

.Lg2_ff2_noissue16:
	ds_read_b128 v[136:139], v158 offset:0
	ds_read_b128 v[140:143], v158 offset:2048
	ds_read_b128 v[144:147], v158 offset:4096
	ds_read_b128 v[148:151], v158 offset:6144
	ds_read_b128 v[164:167], v158 offset:8192
	ds_read_b128 v[168:171], v158 offset:10240
	ds_read_b128 v[172:175], v158 offset:12288
	ds_read_b128 v[176:179], v158 offset:14336
	s_waitcnt lgkmcnt(4)
	v_mfma_f32_16x16x32_bf16 v[0:3], v[200:203], v[136:139], v[0:3]
	v_mfma_f32_16x16x32_bf16 v[4:7], v[208:211], v[136:139], v[4:7]
	v_mfma_f32_16x16x32_bf16 v[8:11], v[200:203], v[140:143], v[8:11]
	v_mfma_f32_16x16x32_bf16 v[12:15], v[208:211], v[140:143], v[12:15]
	v_mfma_f32_16x16x32_bf16 v[16:19], v[200:203], v[144:147], v[16:19]
	v_mfma_f32_16x16x32_bf16 v[20:23], v[208:211], v[144:147], v[20:23]
	v_mfma_f32_16x16x32_bf16 v[24:27], v[200:203], v[148:151], v[24:27]
	v_mfma_f32_16x16x32_bf16 v[28:31], v[208:211], v[148:151], v[28:31]
	ds_read_b128 v[136:139], v158 offset:16384
	ds_read_b128 v[140:143], v158 offset:18432
	ds_read_b128 v[144:147], v158 offset:20480
	ds_read_b128 v[148:151], v158 offset:22528
	s_waitcnt lgkmcnt(4)
	v_mfma_f32_16x16x32_bf16 v[32:35], v[200:203], v[164:167], v[32:35]
	v_mfma_f32_16x16x32_bf16 v[36:39], v[208:211], v[164:167], v[36:39]
	v_mfma_f32_16x16x32_bf16 v[40:43], v[200:203], v[168:171], v[40:43]
	v_mfma_f32_16x16x32_bf16 v[44:47], v[208:211], v[168:171], v[44:47]
	v_mfma_f32_16x16x32_bf16 v[48:51], v[200:203], v[172:175], v[48:51]
	v_mfma_f32_16x16x32_bf16 v[52:55], v[208:211], v[172:175], v[52:55]
	v_mfma_f32_16x16x32_bf16 v[56:59], v[200:203], v[176:179], v[56:59]
	v_mfma_f32_16x16x32_bf16 v[60:63], v[208:211], v[176:179], v[60:63]
	ds_read_b128 v[164:167], v158 offset:24576
	ds_read_b128 v[168:171], v158 offset:26624
	ds_read_b128 v[172:175], v158 offset:28672
	ds_read_b128 v[176:179], v158 offset:30720
	s_waitcnt lgkmcnt(4)
	v_mfma_f32_16x16x32_bf16 v[64:67], v[200:203], v[136:139], v[64:67]
	v_mfma_f32_16x16x32_bf16 v[68:71], v[208:211], v[136:139], v[68:71]
	v_mfma_f32_16x16x32_bf16 v[72:75], v[200:203], v[140:143], v[72:75]
	v_mfma_f32_16x16x32_bf16 v[76:79], v[208:211], v[140:143], v[76:79]
	v_mfma_f32_16x16x32_bf16 v[80:83], v[200:203], v[144:147], v[80:83]
	v_mfma_f32_16x16x32_bf16 v[84:87], v[208:211], v[144:147], v[84:87]
	v_mfma_f32_16x16x32_bf16 v[88:91], v[200:203], v[148:151], v[88:91]
	v_mfma_f32_16x16x32_bf16 v[92:95], v[208:211], v[148:151], v[92:95]
	ds_read_b128 v[136:139], v159 offset:0
	ds_read_b128 v[140:143], v159 offset:2048
	ds_read_b128 v[144:147], v159 offset:4096
	ds_read_b128 v[148:151], v159 offset:6144
	s_waitcnt lgkmcnt(4)
	v_mfma_f32_16x16x32_bf16 v[96:99], v[200:203], v[164:167], v[96:99]
	v_mfma_f32_16x16x32_bf16 v[100:103], v[208:211], v[164:167], v[100:103]
	v_mfma_f32_16x16x32_bf16 v[104:107], v[200:203], v[168:171], v[104:107]
	v_mfma_f32_16x16x32_bf16 v[108:111], v[208:211], v[168:171], v[108:111]
	v_mfma_f32_16x16x32_bf16 v[112:115], v[200:203], v[172:175], v[112:115]
	v_mfma_f32_16x16x32_bf16 v[116:119], v[208:211], v[172:175], v[116:119]
	v_mfma_f32_16x16x32_bf16 v[120:123], v[200:203], v[176:179], v[120:123]
	v_mfma_f32_16x16x32_bf16 v[124:127], v[208:211], v[176:179], v[124:127]
	ds_read_b128 v[164:167], v159 offset:8192
	ds_read_b128 v[168:171], v159 offset:10240
	ds_read_b128 v[172:175], v159 offset:12288
	ds_read_b128 v[176:179], v159 offset:14336
	s_waitcnt lgkmcnt(4)
	v_mfma_f32_16x16x32_bf16 v[0:3], v[204:207], v[136:139], v[0:3]
	v_mfma_f32_16x16x32_bf16 v[4:7], v[240:243], v[136:139], v[4:7]
	v_mfma_f32_16x16x32_bf16 v[8:11], v[204:207], v[140:143], v[8:11]
	v_mfma_f32_16x16x32_bf16 v[12:15], v[240:243], v[140:143], v[12:15]
	v_mfma_f32_16x16x32_bf16 v[16:19], v[204:207], v[144:147], v[16:19]
	v_mfma_f32_16x16x32_bf16 v[20:23], v[240:243], v[144:147], v[20:23]
	v_mfma_f32_16x16x32_bf16 v[24:27], v[204:207], v[148:151], v[24:27]
	v_mfma_f32_16x16x32_bf16 v[28:31], v[240:243], v[148:151], v[28:31]
	ds_read_b128 v[136:139], v159 offset:16384
	ds_read_b128 v[140:143], v159 offset:18432
	ds_read_b128 v[144:147], v159 offset:20480
	ds_read_b128 v[148:151], v159 offset:22528
	s_waitcnt lgkmcnt(4)
	v_mfma_f32_16x16x32_bf16 v[32:35], v[204:207], v[164:167], v[32:35]
	v_mfma_f32_16x16x32_bf16 v[36:39], v[240:243], v[164:167], v[36:39]
	v_mfma_f32_16x16x32_bf16 v[40:43], v[204:207], v[168:171], v[40:43]
	v_mfma_f32_16x16x32_bf16 v[44:47], v[240:243], v[168:171], v[44:47]
	v_mfma_f32_16x16x32_bf16 v[48:51], v[204:207], v[172:175], v[48:51]
	v_mfma_f32_16x16x32_bf16 v[52:55], v[240:243], v[172:175], v[52:55]
	v_mfma_f32_16x16x32_bf16 v[56:59], v[204:207], v[176:179], v[56:59]
	v_mfma_f32_16x16x32_bf16 v[60:63], v[240:243], v[176:179], v[60:63]
	ds_read_b128 v[164:167], v159 offset:24576
	ds_read_b128 v[168:171], v159 offset:26624
	ds_read_b128 v[172:175], v159 offset:28672
	ds_read_b128 v[176:179], v159 offset:30720
	s_waitcnt lgkmcnt(4)
	v_mfma_f32_16x16x32_bf16 v[64:67], v[204:207], v[136:139], v[64:67]
	v_mfma_f32_16x16x32_bf16 v[68:71], v[240:243], v[136:139], v[68:71]
	v_mfma_f32_16x16x32_bf16 v[72:75], v[204:207], v[140:143], v[72:75]
	v_mfma_f32_16x16x32_bf16 v[76:79], v[240:243], v[140:143], v[76:79]
	v_mfma_f32_16x16x32_bf16 v[80:83], v[204:207], v[144:147], v[80:83]
	v_mfma_f32_16x16x32_bf16 v[84:87], v[240:243], v[144:147], v[84:87]
	v_mfma_f32_16x16x32_bf16 v[88:91], v[204:207], v[148:151], v[88:91]
	v_mfma_f32_16x16x32_bf16 v[92:95], v[240:243], v[148:151], v[92:95]
	s_waitcnt lgkmcnt(0)
	v_mfma_f32_16x16x32_bf16 v[96:99], v[204:207], v[164:167], v[96:99]
	v_mfma_f32_16x16x32_bf16 v[100:103], v[240:243], v[164:167], v[100:103]
	v_mfma_f32_16x16x32_bf16 v[104:107], v[204:207], v[168:171], v[104:107]
	v_mfma_f32_16x16x32_bf16 v[108:111], v[240:243], v[168:171], v[108:111]
	v_mfma_f32_16x16x32_bf16 v[112:115], v[204:207], v[172:175], v[112:115]
	v_mfma_f32_16x16x32_bf16 v[116:119], v[240:243], v[172:175], v[116:119]
	v_mfma_f32_16x16x32_bf16 v[120:123], v[204:207], v[176:179], v[120:123]
	v_mfma_f32_16x16x32_bf16 v[124:127], v[240:243], v[176:179], v[124:127]
	s_add_i32 s63, s63, 2
	s_cmp_lt_u32 s63, 64
	s_cbranch_scc1 .Lg2_ff2_loop16
.Lg2_ff2_epi:
	s_nop 7
	s_nop 7
	s_barrier
	v_add_u32_e32 v253, 0x8000, v212
	v_add_u32_e32 v254, 0x8000, v213
	v_cvt_pk_bf16_f32 v0, v0, v1
	v_cvt_pk_bf16_f32 v1, v2, v3
	ds_write_b64 v212, v[0:1] offset:0
	v_cvt_pk_bf16_f32 v4, v4, v5
	v_cvt_pk_bf16_f32 v5, v6, v7
	ds_write_b64 v213, v[4:5] offset:0
	v_cvt_pk_bf16_f32 v8, v8, v9
	v_cvt_pk_bf16_f32 v9, v10, v11
	ds_write_b64 v212, v[8:9] offset:4096
	v_cvt_pk_bf16_f32 v12, v12, v13
	v_cvt_pk_bf16_f32 v13, v14, v15
	ds_write_b64 v213, v[12:13] offset:4096
	v_cvt_pk_bf16_f32 v16, v16, v17
	v_cvt_pk_bf16_f32 v17, v18, v19
	ds_write_b64 v212, v[16:17] offset:8192
	v_cvt_pk_bf16_f32 v20, v20, v21
	v_cvt_pk_bf16_f32 v21, v22, v23
	ds_write_b64 v213, v[20:21] offset:8192
	v_cvt_pk_bf16_f32 v24, v24, v25
	v_cvt_pk_bf16_f32 v25, v26, v27
	ds_write_b64 v212, v[24:25] offset:12288
	v_cvt_pk_bf16_f32 v28, v28, v29
	v_cvt_pk_bf16_f32 v29, v30, v31
	ds_write_b64 v213, v[28:29] offset:12288
	v_cvt_pk_bf16_f32 v32, v32, v33
	v_cvt_pk_bf16_f32 v33, v34, v35
	ds_write_b64 v212, v[32:33] offset:16384
	v_cvt_pk_bf16_f32 v36, v36, v37
	v_cvt_pk_bf16_f32 v37, v38, v39
	ds_write_b64 v213, v[36:37] offset:16384
	v_cvt_pk_bf16_f32 v40, v40, v41
	v_cvt_pk_bf16_f32 v41, v42, v43
	ds_write_b64 v212, v[40:41] offset:20480
	v_cvt_pk_bf16_f32 v44, v44, v45
	v_cvt_pk_bf16_f32 v45, v46, v47
	ds_write_b64 v213, v[44:45] offset:20480
	v_cvt_pk_bf16_f32 v48, v48, v49
	v_cvt_pk_bf16_f32 v49, v50, v51
	ds_write_b64 v212, v[48:49] offset:24576
	v_cvt_pk_bf16_f32 v52, v52, v53
	v_cvt_pk_bf16_f32 v53, v54, v55
	ds_write_b64 v213, v[52:53] offset:24576
	v_cvt_pk_bf16_f32 v56, v56, v57
	v_cvt_pk_bf16_f32 v57, v58, v59
	ds_write_b64 v212, v[56:57] offset:28672
	v_cvt_pk_bf16_f32 v60, v60, v61
	v_cvt_pk_bf16_f32 v61, v62, v63
	ds_write_b64 v213, v[60:61] offset:28672
	v_cvt_pk_bf16_f32 v64, v64, v65
	v_cvt_pk_bf16_f32 v65, v66, v67
	ds_write_b64 v253, v[64:65] offset:0
	v_cvt_pk_bf16_f32 v68, v68, v69
	v_cvt_pk_bf16_f32 v69, v70, v71
	ds_write_b64 v254, v[68:69] offset:0
	v_cvt_pk_bf16_f32 v72, v72, v73
	v_cvt_pk_bf16_f32 v73, v74, v75
	ds_write_b64 v253, v[72:73] offset:4096
	v_cvt_pk_bf16_f32 v76, v76, v77
	v_cvt_pk_bf16_f32 v77, v78, v79
	ds_write_b64 v254, v[76:77] offset:4096
	v_cvt_pk_bf16_f32 v80, v80, v81
	v_cvt_pk_bf16_f32 v81, v82, v83
	ds_write_b64 v253, v[80:81] offset:8192
	v_cvt_pk_bf16_f32 v84, v84, v85
	v_cvt_pk_bf16_f32 v85, v86, v87
	ds_write_b64 v254, v[84:85] offset:8192
	v_cvt_pk_bf16_f32 v88, v88, v89
	v_cvt_pk_bf16_f32 v89, v90, v91
	ds_write_b64 v253, v[88:89] offset:12288
	v_cvt_pk_bf16_f32 v92, v92, v93
	v_cvt_pk_bf16_f32 v93, v94, v95
	ds_write_b64 v254, v[92:93] offset:12288
	v_cvt_pk_bf16_f32 v96, v96, v97
	v_cvt_pk_bf16_f32 v97, v98, v99
	ds_write_b64 v253, v[96:97] offset:16384
	v_cvt_pk_bf16_f32 v100, v100, v101
	v_cvt_pk_bf16_f32 v101, v102, v103
	ds_write_b64 v254, v[100:101] offset:16384
	v_cvt_pk_bf16_f32 v104, v104, v105
	v_cvt_pk_bf16_f32 v105, v106, v107
	ds_write_b64 v253, v[104:105] offset:20480
	v_cvt_pk_bf16_f32 v108, v108, v109
	v_cvt_pk_bf16_f32 v109, v110, v111
	ds_write_b64 v254, v[108:109] offset:20480
	v_cvt_pk_bf16_f32 v112, v112, v113
	v_cvt_pk_bf16_f32 v113, v114, v115
	ds_write_b64 v253, v[112:113] offset:24576
	v_cvt_pk_bf16_f32 v116, v116, v117
	v_cvt_pk_bf16_f32 v117, v118, v119
	ds_write_b64 v254, v[116:117] offset:24576
	v_cvt_pk_bf16_f32 v120, v120, v121
	v_cvt_pk_bf16_f32 v121, v122, v123
	ds_write_b64 v253, v[120:121] offset:28672
	v_cvt_pk_bf16_f32 v124, v124, v125
	v_cvt_pk_bf16_f32 v125, v126, v127
	ds_write_b64 v254, v[124:125] offset:28672
	s_cmp_eq_u32 s65, 0
	s_cbranch_scc1 .Lg2_ff2_st16
	v_cvt_pk_bf16_f32 v128, v128, v129
	v_cvt_pk_bf16_f32 v129, v130, v131
	ds_write_b64 v253, v[128:129] offset:32768
	v_cvt_pk_bf16_f32 v132, v132, v133
	v_cvt_pk_bf16_f32 v133, v134, v135
	ds_write_b64 v254, v[132:133] offset:32768
.Lg2_ff2_st16:
	s_waitcnt lgkmcnt(0)
	s_barrier
	v_add_u32_e32 v255, 0x8000, v247
	ds_read_b128 v[0:3], v247 offset:0
	ds_read_b128 v[4:7], v247 offset:4096
	ds_read_b128 v[8:11], v247 offset:8192
	ds_read_b128 v[12:15], v247 offset:12288
	ds_read_b128 v[16:19], v247 offset:16384
	ds_read_b128 v[20:23], v247 offset:20480
	ds_read_b128 v[24:27], v247 offset:24576
	ds_read_b128 v[28:31], v247 offset:28672
	ds_read_b128 v[32:35], v255 offset:0
	ds_read_b128 v[36:39], v255 offset:4096
	ds_read_b128 v[40:43], v255 offset:8192
	ds_read_b128 v[44:47], v255 offset:12288
	ds_read_b128 v[48:51], v255 offset:16384
	ds_read_b128 v[52:55], v255 offset:20480
	ds_read_b128 v[56:59], v255 offset:24576
	ds_read_b128 v[60:63], v255 offset:28672
	s_cmp_eq_u32 s65, 0
	s_cbranch_scc1 .Lg2_ff2_rd16a
	ds_read_b128 v[64:67], v255 offset:32768
.Lg2_ff2_rd16a:
	s_waitcnt lgkmcnt(0)
	global_store_dwordx4 v252, v[0:3], s[60:61]
	s_add_u32 s60, s60, 0x8000
	s_addc_u32 s61, s61, 0
	global_store_dwordx4 v252, v[4:7], s[60:61]
	s_add_u32 s60, s60, 0x8000
	s_addc_u32 s61, s61, 0
	global_store_dwordx4 v252, v[8:11], s[60:61]
	s_add_u32 s60, s60, 0x8000
	s_addc_u32 s61, s61, 0
	global_store_dwordx4 v252, v[12:15], s[60:61]
	s_add_u32 s60, s60, 0x8000
	s_addc_u32 s61, s61, 0
	global_store_dwordx4 v252, v[16:19], s[60:61]
	s_add_u32 s60, s60, 0x8000
	s_addc_u32 s61, s61, 0
	global_store_dwordx4 v252, v[20:23], s[60:61]
	s_add_u32 s60, s60, 0x8000
	s_addc_u32 s61, s61, 0
	global_store_dwordx4 v252, v[24:27], s[60:61]
	s_add_u32 s60, s60, 0x8000
	s_addc_u32 s61, s61, 0
	global_store_dwordx4 v252, v[28:31], s[60:61]
	s_add_u32 s60, s60, 0x8000
	s_addc_u32 s61, s61, 0
	global_store_dwordx4 v252, v[32:35], s[60:61]
	s_add_u32 s60, s60, 0x8000
	s_addc_u32 s61, s61, 0
	global_store_dwordx4 v252, v[36:39], s[60:61]
	s_add_u32 s60, s60, 0x8000
	s_addc_u32 s61, s61, 0
	global_store_dwordx4 v252, v[40:43], s[60:61]
	s_add_u32 s60, s60, 0x8000
	s_addc_u32 s61, s61, 0
	global_store_dwordx4 v252, v[44:47], s[60:61]
	s_add_u32 s60, s60, 0x8000
	s_addc_u32 s61, s61, 0
	global_store_dwordx4 v252, v[48:51], s[60:61]
	s_add_u32 s60, s60, 0x8000
	s_addc_u32 s61, s61, 0
	global_store_dwordx4 v252, v[52:55], s[60:61]
	s_add_u32 s60, s60, 0x8000
	s_addc_u32 s61, s61, 0
	global_store_dwordx4 v252, v[56:59], s[60:61]
	s_add_u32 s60, s60, 0x8000
	s_addc_u32 s61, s61, 0
	global_store_dwordx4 v252, v[60:63], s[60:61]
	s_add_u32 s60, s60, 0x8000
	s_addc_u32 s61, s61, 0
	s_cmp_eq_u32 s65, 0
	s_cbranch_scc1 .Lg2_ff2_rd16
	global_store_dwordx4 v252, v[64:67], s[60:61]
	s_add_u32 s60, s60, 0x8000
	s_addc_u32 s61, s61, 0
.Lg2_ff2_rd16:
	s_waitcnt lgkmcnt(0)
	s_barrier
	v_mov_b32_e32 v2, 0x10200
	v_mov_b32_e32 v4, s66
	v_mov_b32_e32 v5, s67
	ds_write_b64 v2, v[4:5]
	v_mov_b32_e32 v1, 0
	s_waitcnt vmcnt(0) lgkmcnt(0)

.Lg2_ff1_entry:
	s_waitcnt vmcnt(0) lgkmcnt(0)
	s_barrier
	v_mov_b32_e32 v2, 0x10200
	ds_read_b64 v[2:3], v2
	v_readlane_b32 s0, v246, 0
	v_lshrrev_b32_e32 v4, 6, v163
	v_and_b32_e32 v5, 63, v163
	s_and_b32 s1, s0, 7
	s_lshr_b32 s0, s0, 3
	s_and_b32 s68, s0, 7
	s_lshr_b32 s0, s0, 3
	s_lshl_b32 s0, s0, 3
	s_add_i32 s0, s0, s1
	s_cmp_lt_u32 s0, 32
	s_cselect_b32 s65, 1, 0
	s_min_u32 s1, s0, 32
	s_lshl_b32 s0, s0, 4
	s_add_i32 s0, s0, s1
	s_lshl_b32 s69, s0, 4
	v_readfirstlane_b32 s70, v4
	v_and_b32_e32 v6, 15, v5
	v_lshrrev_b32_e32 v7, 4, v5
	s_waitcnt lgkmcnt(0)
	v_readfirstlane_b32 s66, v2
	v_readfirstlane_b32 s67, v3
	s_lshl_b32 s62, s70, 10
	v_and_b32_e32 v8, 7, v6
	v_xor_b32_e32 v9, v7, v8
	v_lshlrev_b32_e32 v9, 4, v9
	v_lshl_add_u32 v156, v6, 7, v9
	v_add_u32_e32 v10, 4, v7
	v_xor_b32_e32 v10, v10, v8
	v_lshlrev_b32_e32 v10, 4, v10
	v_lshl_add_u32 v157, v6, 7, v10
	v_add_u32_e32 v158, 0x8800, v156
	v_add_u32_e32 v159, 0x8800, v157
	v_lshl_add_u32 v11, v4, 5, v6
	s_mov_b32 s2, 0x800
	v_mul_lo_u32 v11, v11, s2
	v_lshl_add_u32 v160, v7, 4, v11
	v_add_u32_e32 v161, 0x8000, v160
	v_lshrrev_b32_e32 v11, 3, v163
	v_and_b32_e32 v12, 7, v163
	v_and_b32_e32 v13, 7, v11
	v_xor_b32_e32 v12, v12, v13
	v_lshlrev_b32_e32 v12, 4, v12
	s_mov_b32 s2, 0x800
	v_mul_lo_u32 v11, v11, s2
	v_add_u32_e32 v162, v11, v12
	v_lshrrev_b32_e32 v11, 1, v7
	v_lshl_add_u32 v11, v4, 2, v11
	v_xor_b32_e32 v12, v11, v6
	v_lshlrev_b32_e32 v12, 4, v12
	v_and_b32_e32 v13, 1, v7
	v_lshlrev_b32_e32 v13, 3, v13
	v_lshl_add_u32 v14, v6, 8, v13
	v_add_u32_e32 v212, v14, v12
	v_add_u32_e32 v11, 2, v11
	v_xor_b32_e32 v12, v11, v6
	v_lshlrev_b32_e32 v12, 4, v12
	v_add_u32_e32 v213, v14, v12
	v_lshrrev_b32_e32 v11, 4, v163
	v_and_b32_e32 v12, 15, v163
	v_xor_b32_e32 v13, v12, v11
	v_lshlrev_b32_e32 v13, 4, v13
	v_lshl_add_u32 v247, v11, 8, v13
	s_mov_b32 s2, 0x2000
	v_mul_lo_u32 v11, v11, s2
	v_lshl_add_u32 v252, v12, 4, v11
	s_mov_b32 s64, 0
.Lg2_ff1_tile:
	s_lshl_b32 s0, s64, 3
	s_add_i32 s0, s0, s68
	s_lshl_b32 s0, s0, 7
	s_mul_i32 s2, s69, 0x800
	s_mul_hi_u32 s3, s69, 0x800
	s_add_u32 s56, s26, s2
	s_addc_u32 s57, s27, s3
	s_add_u32 s56, s56, 0x13240000
	s_addc_u32 s57, s57, 0
	s_mul_i32 s2, s0, 0x800
	s_mul_hi_u32 s3, s0, 0x800
	s_add_u32 s58, s26, s2
	s_addc_u32 s59, s27, s3
	s_add_u32 s58, s58, 0xff40000
	s_addc_u32 s59, s59, 0
	s_mul_i32 s2, s69, 0x2000
	s_mul_hi_u32 s3, s69, 0x2000
	s_lshl_b32 s0, s0, 1
	s_add_u32 s2, s2, s0
	s_addc_u32 s3, s3, 0
	s_add_u32 s60, s26, s2
	s_addc_u32 s61, s27, s3
	s_add_u32 s60, s60, 0x0
	s_addc_u32 s61, s61, 0
	v_mov_b32_e32 v0, 0
	v_mov_b32_e32 v1, 0
	v_mov_b32_e32 v2, 0
	v_mov_b32_e32 v3, 0
	v_mov_b32_e32 v4, 0
	v_mov_b32_e32 v5, 0
	v_mov_b32_e32 v6, 0
	v_mov_b32_e32 v7, 0
	v_mov_b32_e32 v8, 0
	v_mov_b32_e32 v9, 0
	v_mov_b32_e32 v10, 0
	v_mov_b32_e32 v11, 0
	v_mov_b32_e32 v12, 0
	v_mov_b32_e32 v13, 0
	v_mov_b32_e32 v14, 0
	v_mov_b32_e32 v15, 0
	v_mov_b32_e32 v16, 0
	v_mov_b32_e32 v17, 0
	v_mov_b32_e32 v18, 0
	v_mov_b32_e32 v19, 0
	v_mov_b32_e32 v20, 0
	v_mov_b32_e32 v21, 0
	v_mov_b32_e32 v22, 0
	v_mov_b32_e32 v23, 0
	v_mov_b32_e32 v24, 0
	v_mov_b32_e32 v25, 0
	v_mov_b32_e32 v26, 0
	v_mov_b32_e32 v27, 0
	v_mov_b32_e32 v28, 0
	v_mov_b32_e32 v29, 0
	v_mov_b32_e32 v30, 0
	v_mov_b32_e32 v31, 0
	v_mov_b32_e32 v32, 0
	v_mov_b32_e32 v33, 0
	v_mov_b32_e32 v34, 0
	v_mov_b32_e32 v35, 0
	v_mov_b32_e32 v36, 0
	v_mov_b32_e32 v37, 0
	v_mov_b32_e32 v38, 0
	v_mov_b32_e32 v39, 0
	v_mov_b32_e32 v40, 0
	v_mov_b32_e32 v41, 0
	v_mov_b32_e32 v42, 0
	v_mov_b32_e32 v43, 0
	v_mov_b32_e32 v44, 0
	v_mov_b32_e32 v45, 0
	v_mov_b32_e32 v46, 0
	v_mov_b32_e32 v47, 0
	v_mov_b32_e32 v48, 0
	v_mov_b32_e32 v49, 0
	v_mov_b32_e32 v50, 0
	v_mov_b32_e32 v51, 0
	v_mov_b32_e32 v52, 0
	v_mov_b32_e32 v53, 0
	v_mov_b32_e32 v54, 0
	v_mov_b32_e32 v55, 0
	v_mov_b32_e32 v56, 0
	v_mov_b32_e32 v57, 0
	v_mov_b32_e32 v58, 0
	v_mov_b32_e32 v59, 0
	v_mov_b32_e32 v60, 0
	v_mov_b32_e32 v61, 0
	v_mov_b32_e32 v62, 0
	v_mov_b32_e32 v63, 0
	v_mov_b32_e32 v64, 0
	v_mov_b32_e32 v65, 0
	v_mov_b32_e32 v66, 0
	v_mov_b32_e32 v67, 0
	v_mov_b32_e32 v68, 0
	v_mov_b32_e32 v69, 0
	v_mov_b32_e32 v70, 0
	v_mov_b32_e32 v71, 0
	v_mov_b32_e32 v72, 0
	v_mov_b32_e32 v73, 0
	v_mov_b32_e32 v74, 0
	v_mov_b32_e32 v75, 0
	v_mov_b32_e32 v76, 0
	v_mov_b32_e32 v77, 0
	v_mov_b32_e32 v78, 0
	v_mov_b32_e32 v79, 0
	v_mov_b32_e32 v80, 0
	v_mov_b32_e32 v81, 0
	v_mov_b32_e32 v82, 0
	v_mov_b32_e32 v83, 0
	v_mov_b32_e32 v84, 0
	v_mov_b32_e32 v85, 0
	v_mov_b32_e32 v86, 0
	v_mov_b32_e32 v87, 0
	v_mov_b32_e32 v88, 0
	v_mov_b32_e32 v89, 0
	v_mov_b32_e32 v90, 0
	v_mov_b32_e32 v91, 0
	v_mov_b32_e32 v92, 0
	v_mov_b32_e32 v93, 0
	v_mov_b32_e32 v94, 0
	v_mov_b32_e32 v95, 0
	v_mov_b32_e32 v96, 0
	v_mov_b32_e32 v97, 0
	v_mov_b32_e32 v98, 0
	v_mov_b32_e32 v99, 0
	v_mov_b32_e32 v100, 0
	v_mov_b32_e32 v101, 0
	v_mov_b32_e32 v102, 0
	v_mov_b32_e32 v103, 0
	v_mov_b32_e32 v104, 0
	v_mov_b32_e32 v105, 0
	v_mov_b32_e32 v106, 0
	v_mov_b32_e32 v107, 0
	v_mov_b32_e32 v108, 0
	v_mov_b32_e32 v109, 0
	v_mov_b32_e32 v110, 0
	v_mov_b32_e32 v111, 0
	v_mov_b32_e32 v112, 0
	v_mov_b32_e32 v113, 0
	v_mov_b32_e32 v114, 0
	v_mov_b32_e32 v115, 0
	v_mov_b32_e32 v116, 0
	v_mov_b32_e32 v117, 0
	v_mov_b32_e32 v118, 0
	v_mov_b32_e32 v119, 0
	v_mov_b32_e32 v120, 0
	v_mov_b32_e32 v121, 0
	v_mov_b32_e32 v122, 0
	v_mov_b32_e32 v123, 0
	v_mov_b32_e32 v124, 0
	v_mov_b32_e32 v125, 0
	v_mov_b32_e32 v126, 0
	v_mov_b32_e32 v127, 0
	v_mov_b32_e32 v128, 0
	v_mov_b32_e32 v129, 0
	v_mov_b32_e32 v130, 0
	v_mov_b32_e32 v131, 0
	v_mov_b32_e32 v132, 0
	v_mov_b32_e32 v133, 0
	v_mov_b32_e32 v134, 0
	v_mov_b32_e32 v135, 0
	s_add_u32 s4, s56, 0x0
	s_addc_u32 s5, s57, 0
	s_add_u32 m0, s62, 0x0
	s_nop 0
	global_load_lds_dwordx4 v162, s[4:5]
	s_add_u32 s4, s56, 0x10000
	s_addc_u32 s5, s57, 0
	s_add_u32 m0, s62, 0x1000
	s_nop 0
	global_load_lds_dwordx4 v162, s[4:5]
	s_add_u32 s4, s56, 0x20000
	s_addc_u32 s5, s57, 0
	s_add_u32 m0, s62, 0x2000
	s_nop 0
	global_load_lds_dwordx4 v162, s[4:5]
	s_add_u32 s4, s56, 0x30000
	s_addc_u32 s5, s57, 0
	s_add_u32 m0, s62, 0x3000
	s_nop 0
	global_load_lds_dwordx4 v162, s[4:5]
	s_add_u32 s4, s56, 0x40000
	s_addc_u32 s5, s57, 0
	s_add_u32 m0, s62, 0x4000
	s_nop 0
	global_load_lds_dwordx4 v162, s[4:5]
	s_add_u32 s4, s56, 0x50000
	s_addc_u32 s5, s57, 0
	s_add_u32 m0, s62, 0x5000
	s_nop 0
	global_load_lds_dwordx4 v162, s[4:5]
	s_add_u32 s4, s56, 0x60000
	s_addc_u32 s5, s57, 0
	s_add_u32 m0, s62, 0x6000
	s_nop 0
	global_load_lds_dwordx4 v162, s[4:5]
	s_add_u32 s4, s56, 0x70000
	s_addc_u32 s5, s57, 0
	s_add_u32 m0, s62, 0x7000
	s_nop 0
	global_load_lds_dwordx4 v162, s[4:5]
	s_cmp_eq_u32 s65, 0
	s_cbranch_scc1 .Lg2_ff1_nodma8_0
	s_cmp_gt_u32 s70, 1
	s_cbranch_scc1 .Lg2_ff1_nodma8_0
	s_add_u32 s4, s56, 0x80000
	s_addc_u32 s5, s57, 0
	s_add_u32 m0, s62, 0x8000
	s_nop 0
	global_load_lds_dwordx4 v162, s[4:5]

.Lg2_ff1_loop17:
	s_waitcnt vmcnt(0)
	s_barrier
	s_add_u32 s56, s56, 0x80
	s_addc_u32 s57, s57, 0
	s_add_u32 s58, s58, 0x80
	s_addc_u32 s59, s59, 0
	s_add_u32 s4, s56, 0x0
	s_addc_u32 s5, s57, 0
	s_add_u32 m0, s62, 0x8800
	s_nop 0
	global_load_lds_dwordx4 v162, s[4:5]
	s_add_u32 s4, s56, 0x10000
	s_addc_u32 s5, s57, 0
	s_add_u32 m0, s62, 0x9800
	s_nop 0
	global_load_lds_dwordx4 v162, s[4:5]
	s_add_u32 s4, s56, 0x20000
	s_addc_u32 s5, s57, 0
	s_add_u32 m0, s62, 0xa800
	s_nop 0
	global_load_lds_dwordx4 v162, s[4:5]
	s_add_u32 s4, s56, 0x30000
	s_addc_u32 s5, s57, 0
	s_add_u32 m0, s62, 0xb800
	s_nop 0
	global_load_lds_dwordx4 v162, s[4:5]
	s_add_u32 s4, s56, 0x40000
	s_addc_u32 s5, s57, 0
	s_add_u32 m0, s62, 0xc800
	s_nop 0
	global_load_lds_dwordx4 v162, s[4:5]
	s_add_u32 s4, s56, 0x50000
	s_addc_u32 s5, s57, 0
	s_add_u32 m0, s62, 0xd800
	s_nop 0
	global_load_lds_dwordx4 v162, s[4:5]
	s_add_u32 s4, s56, 0x60000
	s_addc_u32 s5, s57, 0
	s_add_u32 m0, s62, 0xe800
	s_nop 0
	global_load_lds_dwordx4 v162, s[4:5]
	s_add_u32 s4, s56, 0x70000
	s_addc_u32 s5, s57, 0
	s_add_u32 m0, s62, 0xf800
	s_nop 0
	global_load_lds_dwordx4 v162, s[4:5]
	s_cmp_eq_u32 s65, 0
	s_cbranch_scc1 .Lg2_ff1_nodma8_1
	s_cmp_gt_u32 s70, 1
	s_cbranch_scc1 .Lg2_ff1_nodma8_1
	s_add_u32 s4, s56, 0x80000
	s_addc_u32 s5, s57, 0
	s_add_u32 m0, s62, 0x10800
	s_nop 0
	global_load_lds_dwordx4 v162, s[4:5]
.Lg2_ff1_nodma8_1:
	global_load_dwordx4 v[200:203], v160, s[58:59] offset:0
	global_load_dwordx4 v[204:207], v160, s[58:59] offset:64
	global_load_dwordx4 v[208:211], v161, s[58:59] offset:0
	global_load_dwordx4 v[240:243], v161, s[58:59] offset:64
	ds_read_b128 v[136:139], v156 offset:0
	ds_read_b128 v[140:143], v156 offset:2048
	ds_read_b128 v[144:147], v156 offset:4096
	ds_read_b128 v[148:151], v156 offset:6144
	ds_read_b128 v[164:167], v156 offset:8192
	ds_read_b128 v[168:171], v156 offset:10240
	ds_read_b128 v[172:175], v156 offset:12288
	ds_read_b128 v[176:179], v156 offset:14336
	s_waitcnt lgkmcnt(4)
	v_mfma_f32_16x16x32_bf16 v[0:3], v[184:187], v[136:139], v[0:3]
	v_mfma_f32_16x16x32_bf16 v[4:7], v[192:195], v[136:139], v[4:7]
	v_mfma_f32_16x16x32_bf16 v[8:11], v[184:187], v[140:143], v[8:11]
	v_mfma_f32_16x16x32_bf16 v[12:15], v[192:195], v[140:143], v[12:15]
	v_mfma_f32_16x16x32_bf16 v[16:19], v[184:187], v[144:147], v[16:19]
	v_mfma_f32_16x16x32_bf16 v[20:23], v[192:195], v[144:147], v[20:23]
	v_mfma_f32_16x16x32_bf16 v[24:27], v[184:187], v[148:151], v[24:27]
	v_mfma_f32_16x16x32_bf16 v[28:31], v[192:195], v[148:151], v[28:31]
	ds_read_b128 v[136:139], v156 offset:16384
	ds_read_b128 v[140:143], v156 offset:18432
	ds_read_b128 v[144:147], v156 offset:20480
	ds_read_b128 v[148:151], v156 offset:22528
	s_waitcnt lgkmcnt(4)
	v_mfma_f32_16x16x32_bf16 v[32:35], v[184:187], v[164:167], v[32:35]
	v_mfma_f32_16x16x32_bf16 v[36:39], v[192:195], v[164:167], v[36:39]
	v_mfma_f32_16x16x32_bf16 v[40:43], v[184:187], v[168:171], v[40:43]
	v_mfma_f32_16x16x32_bf16 v[44:47], v[192:195], v[168:171], v[44:47]
	v_mfma_f32_16x16x32_bf16 v[48:51], v[184:187], v[172:175], v[48:51]
	v_mfma_f32_16x16x32_bf16 v[52:55], v[192:195], v[172:175], v[52:55]
	v_mfma_f32_16x16x32_bf16 v[56:59], v[184:187], v[176:179], v[56:59]
	v_mfma_f32_16x16x32_bf16 v[60:63], v[192:195], v[176:179], v[60:63]
	ds_read_b128 v[164:167], v156 offset:24576
	ds_read_b128 v[168:171], v156 offset:26624
	ds_read_b128 v[172:175], v156 offset:28672
	ds_read_b128 v[176:179], v156 offset:30720
	ds_read_b128 v[180:183], v156 offset:32768
	s_waitcnt lgkmcnt(5)
	v_mfma_f32_16x16x32_bf16 v[64:67], v[184:187], v[136:139], v[64:67]
	v_mfma_f32_16x16x32_bf16 v[68:71], v[192:195], v[136:139], v[68:71]
	v_mfma_f32_16x16x32_bf16 v[72:75], v[184:187], v[140:143], v[72:75]
	v_mfma_f32_16x16x32_bf16 v[76:79], v[192:195], v[140:143], v[76:79]
	v_mfma_f32_16x16x32_bf16 v[80:83], v[184:187], v[144:147], v[80:83]
	v_mfma_f32_16x16x32_bf16 v[84:87], v[192:195], v[144:147], v[84:87]
	v_mfma_f32_16x16x32_bf16 v[88:91], v[184:187], v[148:151], v[88:91]
	v_mfma_f32_16x16x32_bf16 v[92:95], v[192:195], v[148:151], v[92:95]
	ds_read_b128 v[136:139], v157 offset:0
	ds_read_b128 v[140:143], v157 offset:2048
	ds_read_b128 v[144:147], v157 offset:4096
	ds_read_b128 v[148:151], v157 offset:6144
	s_waitcnt lgkmcnt(4)
	v_mfma_f32_16x16x32_bf16 v[96:99], v[184:187], v[164:167], v[96:99]
	v_mfma_f32_16x16x32_bf16 v[100:103], v[192:195], v[164:167], v[100:103]
	v_mfma_f32_16x16x32_bf16 v[104:107], v[184:187], v[168:171], v[104:107]
	v_mfma_f32_16x16x32_bf16 v[108:111], v[192:195], v[168:171], v[108:111]
	v_mfma_f32_16x16x32_bf16 v[112:115], v[184:187], v[172:175], v[112:115]
	v_mfma_f32_16x16x32_bf16 v[116:119], v[192:195], v[172:175], v[116:119]
	v_mfma_f32_16x16x32_bf16 v[120:123], v[184:187], v[176:179], v[120:123]
	v_mfma_f32_16x16x32_bf16 v[124:127], v[192:195], v[176:179], v[124:127]
	v_mfma_f32_16x16x32_bf16 v[128:131], v[184:187], v[180:183], v[128:131]
	v_mfma_f32_16x16x32_bf16 v[132:135], v[192:195], v[180:183], v[132:135]
	ds_read_b128 v[164:167], v157 offset:8192
	ds_read_b128 v[168:171], v157 offset:10240
	ds_read_b128 v[172:175], v157 offset:12288
	ds_read_b128 v[176:179], v157 offset:14336
	s_waitcnt lgkmcnt(4)
	v_mfma_f32_16x16x32_bf16 v[0:3], v[188:191], v[136:139], v[0:3]
	v_mfma_f32_16x16x32_bf16 v[4:7], v[196:199], v[136:139], v[4:7]
	v_mfma_f32_16x16x32_bf16 v[8:11], v[188:191], v[140:143], v[8:11]
	v_mfma_f32_16x16x32_bf16 v[12:15], v[196:199], v[140:143], v[12:15]
	v_mfma_f32_16x16x32_bf16 v[16:19], v[188:191], v[144:147], v[16:19]
	v_mfma_f32_16x16x32_bf16 v[20:23], v[196:199], v[144:147], v[20:23]
	v_mfma_f32_16x16x32_bf16 v[24:27], v[188:191], v[148:151], v[24:27]
	v_mfma_f32_16x16x32_bf16 v[28:31], v[196:199], v[148:151], v[28:31]
	ds_read_b128 v[136:139], v157 offset:16384
	ds_read_b128 v[140:143], v157 offset:18432
	ds_read_b128 v[144:147], v157 offset:20480
	ds_read_b128 v[148:151], v157 offset:22528
	s_waitcnt lgkmcnt(4)
	v_mfma_f32_16x16x32_bf16 v[32:35], v[188:191], v[164:167], v[32:35]
	v_mfma_f32_16x16x32_bf16 v[36:39], v[196:199], v[164:167], v[36:39]
	v_mfma_f32_16x16x32_bf16 v[40:43], v[188:191], v[168:171], v[40:43]
	v_mfma_f32_16x16x32_bf16 v[44:47], v[196:199], v[168:171], v[44:47]
	v_mfma_f32_16x16x32_bf16 v[48:51], v[188:191], v[172:175], v[48:51]
	v_mfma_f32_16x16x32_bf16 v[52:55], v[196:199], v[172:175], v[52:55]
	v_mfma_f32_16x16x32_bf16 v[56:59], v[188:191], v[176:179], v[56:59]
	v_mfma_f32_16x16x32_bf16 v[60:63], v[196:199], v[176:179], v[60:63]
	ds_read_b128 v[164:167], v157 offset:24576
	ds_read_b128 v[168:171], v157 offset:26624
	ds_read_b128 v[172:175], v157 offset:28672
	ds_read_b128 v[176:179], v157 offset:30720
	ds_read_b128 v[180:183], v157 offset:32768
	s_waitcnt lgkmcnt(5)
	v_mfma_f32_16x16x32_bf16 v[64:67], v[188:191], v[136:139], v[64:67]
	v_mfma_f32_16x16x32_bf16 v[68:71], v[196:199], v[136:139], v[68:71]
	v_mfma_f32_16x16x32_bf16 v[72:75], v[188:191], v[140:143], v[72:75]
	v_mfma_f32_16x16x32_bf16 v[76:79], v[196:199], v[140:143], v[76:79]
	v_mfma_f32_16x16x32_bf16 v[80:83], v[188:191], v[144:147], v[80:83]
	v_mfma_f32_16x16x32_bf16 v[84:87], v[196:199], v[144:147], v[84:87]
	v_mfma_f32_16x16x32_bf16 v[88:91], v[188:191], v[148:151], v[88:91]
	v_mfma_f32_16x16x32_bf16 v[92:95], v[196:199], v[148:151], v[92:95]
	s_waitcnt lgkmcnt(0)
	v_mfma_f32_16x16x32_bf16 v[96:99], v[188:191], v[164:167], v[96:99]
	v_mfma_f32_16x16x32_bf16 v[100:103], v[196:199], v[164:167], v[100:103]
	v_mfma_f32_16x16x32_bf16 v[104:107], v[188:191], v[168:171], v[104:107]
	v_mfma_f32_16x16x32_bf16 v[108:111], v[196:199], v[168:171], v[108:111]
	v_mfma_f32_16x16x32_bf16 v[112:115], v[188:191], v[172:175], v[112:115]
	v_mfma_f32_16x16x32_bf16 v[116:119], v[196:199], v[172:175], v[116:119]
	v_mfma_f32_16x16x32_bf16 v[120:123], v[188:191], v[176:179], v[120:123]
	v_mfma_f32_16x16x32_bf16 v[124:127], v[196:199], v[176:179], v[124:127]
	v_mfma_f32_16x16x32_bf16 v[128:131], v[188:191], v[180:183], v[128:131]
	v_mfma_f32_16x16x32_bf16 v[132:135], v[196:199], v[180:183], v[132:135]
	s_waitcnt vmcnt(0)
	s_barrier
	s_cmp_ge_u32 s63, 14
	s_cbranch_scc1 .Lg2_ff1_noissue17
	s_add_u32 s56, s56, 0x80
	s_addc_u32 s57, s57, 0
	s_add_u32 s58, s58, 0x80
	s_addc_u32 s59, s59, 0
	s_add_u32 s4, s56, 0x0
	s_addc_u32 s5, s57, 0
	s_add_u32 m0, s62, 0x0
	s_nop 0
	global_load_lds_dwordx4 v162, s[4:5]
	s_add_u32 s4, s56, 0x10000
	s_addc_u32 s5, s57, 0
	s_add_u32 m0, s62, 0x1000
	s_nop 0
	global_load_lds_dwordx4 v162, s[4:5]
	s_add_u32 s4, s56, 0x20000
	s_addc_u32 s5, s57, 0
	s_add_u32 m0, s62, 0x2000
	s_nop 0
	global_load_lds_dwordx4 v162, s[4:5]
	s_add_u32 s4, s56, 0x30000
	s_addc_u32 s5, s57, 0
	s_add_u32 m0, s62, 0x3000
	s_nop 0
	global_load_lds_dwordx4 v162, s[4:5]
	s_add_u32 s4, s56, 0x40000
	s_addc_u32 s5, s57, 0
	s_add_u32 m0, s62, 0x4000
	s_nop 0
	global_load_lds_dwordx4 v162, s[4:5]
	s_add_u32 s4, s56, 0x50000
	s_addc_u32 s5, s57, 0
	s_add_u32 m0, s62, 0x5000
	s_nop 0
	global_load_lds_dwordx4 v162, s[4:5]
	s_add_u32 s4, s56, 0x60000
	s_addc_u32 s5, s57, 0
	s_add_u32 m0, s62, 0x6000
	s_nop 0
	global_load_lds_dwordx4 v162, s[4:5]
	s_add_u32 s4, s56, 0x70000
	s_addc_u32 s5, s57, 0
	s_add_u32 m0, s62, 0x7000
	s_nop 0
	global_load_lds_dwordx4 v162, s[4:5]
	s_cmp_eq_u32 s65, 0
	s_cbranch_scc1 .Lg2_ff1_nodma8_2
	s_cmp_gt_u32 s70, 1
	s_cbranch_scc1 .Lg2_ff1_nodma8_2
	s_add_u32 s4, s56, 0x80000
	s_addc_u32 s5, s57, 0
	s_add_u32 m0, s62, 0x8000
	s_nop 0
	global_load_lds_dwordx4 v162, s[4:5]

.Lg2_ff1_noissue17:
	ds_read_b128 v[136:139], v158 offset:0
	ds_read_b128 v[140:143], v158 offset:2048
	ds_read_b128 v[144:147], v158 offset:4096
	ds_read_b128 v[148:151], v158 offset:6144
	ds_read_b128 v[164:167], v158 offset:8192
	ds_read_b128 v[168:171], v158 offset:10240
	ds_read_b128 v[172:175], v158 offset:12288
	ds_read_b128 v[176:179], v158 offset:14336
	s_waitcnt lgkmcnt(4)
	v_mfma_f32_16x16x32_bf16 v[0:3], v[200:203], v[136:139], v[0:3]
	v_mfma_f32_16x16x32_bf16 v[4:7], v[208:211], v[136:139], v[4:7]
	v_mfma_f32_16x16x32_bf16 v[8:11], v[200:203], v[140:143], v[8:11]
	v_mfma_f32_16x16x32_bf16 v[12:15], v[208:211], v[140:143], v[12:15]
	v_mfma_f32_16x16x32_bf16 v[16:19], v[200:203], v[144:147], v[16:19]
	v_mfma_f32_16x16x32_bf16 v[20:23], v[208:211], v[144:147], v[20:23]
	v_mfma_f32_16x16x32_bf16 v[24:27], v[200:203], v[148:151], v[24:27]
	v_mfma_f32_16x16x32_bf16 v[28:31], v[208:211], v[148:151], v[28:31]
	ds_read_b128 v[136:139], v158 offset:16384
	ds_read_b128 v[140:143], v158 offset:18432
	ds_read_b128 v[144:147], v158 offset:20480
	ds_read_b128 v[148:151], v158 offset:22528
	s_waitcnt lgkmcnt(4)
	v_mfma_f32_16x16x32_bf16 v[32:35], v[200:203], v[164:167], v[32:35]
	v_mfma_f32_16x16x32_bf16 v[36:39], v[208:211], v[164:167], v[36:39]
	v_mfma_f32_16x16x32_bf16 v[40:43], v[200:203], v[168:171], v[40:43]
	v_mfma_f32_16x16x32_bf16 v[44:47], v[208:211], v[168:171], v[44:47]
	v_mfma_f32_16x16x32_bf16 v[48:51], v[200:203], v[172:175], v[48:51]
	v_mfma_f32_16x16x32_bf16 v[52:55], v[208:211], v[172:175], v[52:55]
	v_mfma_f32_16x16x32_bf16 v[56:59], v[200:203], v[176:179], v[56:59]
	v_mfma_f32_16x16x32_bf16 v[60:63], v[208:211], v[176:179], v[60:63]
	ds_read_b128 v[164:167], v158 offset:24576
	ds_read_b128 v[168:171], v158 offset:26624
	ds_read_b128 v[172:175], v158 offset:28672
	ds_read_b128 v[176:179], v158 offset:30720
	ds_read_b128 v[180:183], v158 offset:32768
	s_waitcnt lgkmcnt(5)
	v_mfma_f32_16x16x32_bf16 v[64:67], v[200:203], v[136:139], v[64:67]
	v_mfma_f32_16x16x32_bf16 v[68:71], v[208:211], v[136:139], v[68:71]
	v_mfma_f32_16x16x32_bf16 v[72:75], v[200:203], v[140:143], v[72:75]
	v_mfma_f32_16x16x32_bf16 v[76:79], v[208:211], v[140:143], v[76:79]
	v_mfma_f32_16x16x32_bf16 v[80:83], v[200:203], v[144:147], v[80:83]
	v_mfma_f32_16x16x32_bf16 v[84:87], v[208:211], v[144:147], v[84:87]
	v_mfma_f32_16x16x32_bf16 v[88:91], v[200:203], v[148:151], v[88:91]
	v_mfma_f32_16x16x32_bf16 v[92:95], v[208:211], v[148:151], v[92:95]
	ds_read_b128 v[136:139], v159 offset:0
	ds_read_b128 v[140:143], v159 offset:2048
	ds_read_b128 v[144:147], v159 offset:4096
	ds_read_b128 v[148:151], v159 offset:6144
	s_waitcnt lgkmcnt(4)
	v_mfma_f32_16x16x32_bf16 v[96:99], v[200:203], v[164:167], v[96:99]
	v_mfma_f32_16x16x32_bf16 v[100:103], v[208:211], v[164:167], v[100:103]
	v_mfma_f32_16x16x32_bf16 v[104:107], v[200:203], v[168:171], v[104:107]
	v_mfma_f32_16x16x32_bf16 v[108:111], v[208:211], v[168:171], v[108:111]
	v_mfma_f32_16x16x32_bf16 v[112:115], v[200:203], v[172:175], v[112:115]
	v_mfma_f32_16x16x32_bf16 v[116:119], v[208:211], v[172:175], v[116:119]
	v_mfma_f32_16x16x32_bf16 v[120:123], v[200:203], v[176:179], v[120:123]
	v_mfma_f32_16x16x32_bf16 v[124:127], v[208:211], v[176:179], v[124:127]
	v_mfma_f32_16x16x32_bf16 v[128:131], v[200:203], v[180:183], v[128:131]
	v_mfma_f32_16x16x32_bf16 v[132:135], v[208:211], v[180:183], v[132:135]
	ds_read_b128 v[164:167], v159 offset:8192
	ds_read_b128 v[168:171], v159 offset:10240
	ds_read_b128 v[172:175], v159 offset:12288
	ds_read_b128 v[176:179], v159 offset:14336
	s_waitcnt lgkmcnt(4)
	v_mfma_f32_16x16x32_bf16 v[0:3], v[204:207], v[136:139], v[0:3]
	v_mfma_f32_16x16x32_bf16 v[4:7], v[240:243], v[136:139], v[4:7]
	v_mfma_f32_16x16x32_bf16 v[8:11], v[204:207], v[140:143], v[8:11]
	v_mfma_f32_16x16x32_bf16 v[12:15], v[240:243], v[140:143], v[12:15]
	v_mfma_f32_16x16x32_bf16 v[16:19], v[204:207], v[144:147], v[16:19]
	v_mfma_f32_16x16x32_bf16 v[20:23], v[240:243], v[144:147], v[20:23]
	v_mfma_f32_16x16x32_bf16 v[24:27], v[204:207], v[148:151], v[24:27]
	v_mfma_f32_16x16x32_bf16 v[28:31], v[240:243], v[148:151], v[28:31]
	ds_read_b128 v[136:139], v159 offset:16384
	ds_read_b128 v[140:143], v159 offset:18432
	ds_read_b128 v[144:147], v159 offset:20480
	ds_read_b128 v[148:151], v159 offset:22528
	s_waitcnt lgkmcnt(4)
	v_mfma_f32_16x16x32_bf16 v[32:35], v[204:207], v[164:167], v[32:35]
	v_mfma_f32_16x16x32_bf16 v[36:39], v[240:243], v[164:167], v[36:39]
	v_mfma_f32_16x16x32_bf16 v[40:43], v[204:207], v[168:171], v[40:43]
	v_mfma_f32_16x16x32_bf16 v[44:47], v[240:243], v[168:171], v[44:47]
	v_mfma_f32_16x16x32_bf16 v[48:51], v[204:207], v[172:175], v[48:51]
	v_mfma_f32_16x16x32_bf16 v[52:55], v[240:243], v[172:175], v[52:55]
	v_mfma_f32_16x16x32_bf16 v[56:59], v[204:207], v[176:179], v[56:59]
	v_mfma_f32_16x16x32_bf16 v[60:63], v[240:243], v[176:179], v[60:63]
	ds_read_b128 v[164:167], v159 offset:24576
	ds_read_b128 v[168:171], v159 offset:26624
	ds_read_b128 v[172:175], v159 offset:28672
	ds_read_b128 v[176:179], v159 offset:30720
	ds_read_b128 v[180:183], v159 offset:32768
	s_waitcnt lgkmcnt(5)
	v_mfma_f32_16x16x32_bf16 v[64:67], v[204:207], v[136:139], v[64:67]
	v_mfma_f32_16x16x32_bf16 v[68:71], v[240:243], v[136:139], v[68:71]
	v_mfma_f32_16x16x32_bf16 v[72:75], v[204:207], v[140:143], v[72:75]
	v_mfma_f32_16x16x32_bf16 v[76:79], v[240:243], v[140:143], v[76:79]
	v_mfma_f32_16x16x32_bf16 v[80:83], v[204:207], v[144:147], v[80:83]
	v_mfma_f32_16x16x32_bf16 v[84:87], v[240:243], v[144:147], v[84:87]
	v_mfma_f32_16x16x32_bf16 v[88:91], v[204:207], v[148:151], v[88:91]
	v_mfma_f32_16x16x32_bf16 v[92:95], v[240:243], v[148:151], v[92:95]
	s_waitcnt lgkmcnt(0)
	v_mfma_f32_16x16x32_bf16 v[96:99], v[204:207], v[164:167], v[96:99]
	v_mfma_f32_16x16x32_bf16 v[100:103], v[240:243], v[164:167], v[100:103]
	v_mfma_f32_16x16x32_bf16 v[104:107], v[204:207], v[168:171], v[104:107]
	v_mfma_f32_16x16x32_bf16 v[108:111], v[240:243], v[168:171], v[108:111]
	v_mfma_f32_16x16x32_bf16 v[112:115], v[204:207], v[172:175], v[112:115]
	v_mfma_f32_16x16x32_bf16 v[116:119], v[240:243], v[172:175], v[116:119]
	v_mfma_f32_16x16x32_bf16 v[120:123], v[204:207], v[176:179], v[120:123]
	v_mfma_f32_16x16x32_bf16 v[124:127], v[240:243], v[176:179], v[124:127]
	v_mfma_f32_16x16x32_bf16 v[128:131], v[204:207], v[180:183], v[128:131]
	v_mfma_f32_16x16x32_bf16 v[132:135], v[240:243], v[180:183], v[132:135]
	s_add_i32 s63, s63, 2
	s_cmp_lt_u32 s63, 16
	s_cbranch_scc1 .Lg2_ff1_loop17
	s_branch .Lg2_ff1_epi

.Lg2_ff1_nodma8_3:
	global_load_dwordx4 v[200:203], v160, s[58:59] offset:0
	global_load_dwordx4 v[204:207], v160, s[58:59] offset:64
	global_load_dwordx4 v[208:211], v161, s[58:59] offset:0
	global_load_dwordx4 v[240:243], v161, s[58:59] offset:64
	ds_read_b128 v[136:139], v156 offset:0
	ds_read_b128 v[140:143], v156 offset:2048
	ds_read_b128 v[144:147], v156 offset:4096
	ds_read_b128 v[148:151], v156 offset:6144
	ds_read_b128 v[164:167], v156 offset:8192
	ds_read_b128 v[168:171], v156 offset:10240
	ds_read_b128 v[172:175], v156 offset:12288
	ds_read_b128 v[176:179], v156 offset:14336
	s_waitcnt lgkmcnt(4)
	v_mfma_f32_16x16x32_bf16 v[0:3], v[184:187], v[136:139], v[0:3]
	v_mfma_f32_16x16x32_bf16 v[4:7], v[192:195], v[136:139], v[4:7]
	v_mfma_f32_16x16x32_bf16 v[8:11], v[184:187], v[140:143], v[8:11]
	v_mfma_f32_16x16x32_bf16 v[12:15], v[192:195], v[140:143], v[12:15]
	v_mfma_f32_16x16x32_bf16 v[16:19], v[184:187], v[144:147], v[16:19]
	v_mfma_f32_16x16x32_bf16 v[20:23], v[192:195], v[144:147], v[20:23]
	v_mfma_f32_16x16x32_bf16 v[24:27], v[184:187], v[148:151], v[24:27]
	v_mfma_f32_16x16x32_bf16 v[28:31], v[192:195], v[148:151], v[28:31]
	ds_read_b128 v[136:139], v156 offset:16384
	ds_read_b128 v[140:143], v156 offset:18432
	ds_read_b128 v[144:147], v156 offset:20480
	ds_read_b128 v[148:151], v156 offset:22528
	s_waitcnt lgkmcnt(4)
	v_mfma_f32_16x16x32_bf16 v[32:35], v[184:187], v[164:167], v[32:35]
	v_mfma_f32_16x16x32_bf16 v[36:39], v[192:195], v[164:167], v[36:39]
	v_mfma_f32_16x16x32_bf16 v[40:43], v[184:187], v[168:171], v[40:43]
	v_mfma_f32_16x16x32_bf16 v[44:47], v[192:195], v[168:171], v[44:47]
	v_mfma_f32_16x16x32_bf16 v[48:51], v[184:187], v[172:175], v[48:51]
	v_mfma_f32_16x16x32_bf16 v[52:55], v[192:195], v[172:175], v[52:55]
	v_mfma_f32_16x16x32_bf16 v[56:59], v[184:187], v[176:179], v[56:59]
	v_mfma_f32_16x16x32_bf16 v[60:63], v[192:195], v[176:179], v[60:63]
	ds_read_b128 v[164:167], v156 offset:24576
	ds_read_b128 v[168:171], v156 offset:26624
	ds_read_b128 v[172:175], v156 offset:28672
	ds_read_b128 v[176:179], v156 offset:30720
	s_waitcnt lgkmcnt(4)
	v_mfma_f32_16x16x32_bf16 v[64:67], v[184:187], v[136:139], v[64:67]
	v_mfma_f32_16x16x32_bf16 v[68:71], v[192:195], v[136:139], v[68:71]
	v_mfma_f32_16x16x32_bf16 v[72:75], v[184:187], v[140:143], v[72:75]
	v_mfma_f32_16x16x32_bf16 v[76:79], v[192:195], v[140:143], v[76:79]
	v_mfma_f32_16x16x32_bf16 v[80:83], v[184:187], v[144:147], v[80:83]
	v_mfma_f32_16x16x32_bf16 v[84:87], v[192:195], v[144:147], v[84:87]
	v_mfma_f32_16x16x32_bf16 v[88:91], v[184:187], v[148:151], v[88:91]
	v_mfma_f32_16x16x32_bf16 v[92:95], v[192:195], v[148:151], v[92:95]
	ds_read_b128 v[136:139], v157 offset:0
	ds_read_b128 v[140:143], v157 offset:2048
	ds_read_b128 v[144:147], v157 offset:4096
	ds_read_b128 v[148:151], v157 offset:6144
	s_waitcnt lgkmcnt(4)
	v_mfma_f32_16x16x32_bf16 v[96:99], v[184:187], v[164:167], v[96:99]
	v_mfma_f32_16x16x32_bf16 v[100:103], v[192:195], v[164:167], v[100:103]
	v_mfma_f32_16x16x32_bf16 v[104:107], v[184:187], v[168:171], v[104:107]
	v_mfma_f32_16x16x32_bf16 v[108:111], v[192:195], v[168:171], v[108:111]
	v_mfma_f32_16x16x32_bf16 v[112:115], v[184:187], v[172:175], v[112:115]
	v_mfma_f32_16x16x32_bf16 v[116:119], v[192:195], v[172:175], v[116:119]
	v_mfma_f32_16x16x32_bf16 v[120:123], v[184:187], v[176:179], v[120:123]
	v_mfma_f32_16x16x32_bf16 v[124:127], v[192:195], v[176:179], v[124:127]
	ds_read_b128 v[164:167], v157 offset:8192
	ds_read_b128 v[168:171], v157 offset:10240
	ds_read_b128 v[172:175], v157 offset:12288
	ds_read_b128 v[176:179], v157 offset:14336
	s_waitcnt lgkmcnt(4)
	v_mfma_f32_16x16x32_bf16 v[0:3], v[188:191], v[136:139], v[0:3]
	v_mfma_f32_16x16x32_bf16 v[4:7], v[196:199], v[136:139], v[4:7]
	v_mfma_f32_16x16x32_bf16 v[8:11], v[188:191], v[140:143], v[8:11]
	v_mfma_f32_16x16x32_bf16 v[12:15], v[196:199], v[140:143], v[12:15]
	v_mfma_f32_16x16x32_bf16 v[16:19], v[188:191], v[144:147], v[16:19]
	v_mfma_f32_16x16x32_bf16 v[20:23], v[196:199], v[144:147], v[20:23]
	v_mfma_f32_16x16x32_bf16 v[24:27], v[188:191], v[148:151], v[24:27]
	v_mfma_f32_16x16x32_bf16 v[28:31], v[196:199], v[148:151], v[28:31]
	ds_read_b128 v[136:139], v157 offset:16384
	ds_read_b128 v[140:143], v157 offset:18432
	ds_read_b128 v[144:147], v157 offset:20480
	ds_read_b128 v[148:151], v157 offset:22528
	s_waitcnt lgkmcnt(4)
	v_mfma_f32_16x16x32_bf16 v[32:35], v[188:191], v[164:167], v[32:35]
	v_mfma_f32_16x16x32_bf16 v[36:39], v[196:199], v[164:167], v[36:39]
	v_mfma_f32_16x16x32_bf16 v[40:43], v[188:191], v[168:171], v[40:43]
	v_mfma_f32_16x16x32_bf16 v[44:47], v[196:199], v[168:171], v[44:47]
	v_mfma_f32_16x16x32_bf16 v[48:51], v[188:191], v[172:175], v[48:51]
	v_mfma_f32_16x16x32_bf16 v[52:55], v[196:199], v[172:175], v[52:55]
	v_mfma_f32_16x16x32_bf16 v[56:59], v[188:191], v[176:179], v[56:59]
	v_mfma_f32_16x16x32_bf16 v[60:63], v[196:199], v[176:179], v[60:63]
	ds_read_b128 v[164:167], v157 offset:24576
	ds_read_b128 v[168:171], v157 offset:26624
	ds_read_b128 v[172:175], v157 offset:28672
	ds_read_b128 v[176:179], v157 offset:30720
	s_waitcnt lgkmcnt(4)
	v_mfma_f32_16x16x32_bf16 v[64:67], v[188:191], v[136:139], v[64:67]
	v_mfma_f32_16x16x32_bf16 v[68:71], v[196:199], v[136:139], v[68:71]
	v_mfma_f32_16x16x32_bf16 v[72:75], v[188:191], v[140:143], v[72:75]
	v_mfma_f32_16x16x32_bf16 v[76:79], v[196:199], v[140:143], v[76:79]
	v_mfma_f32_16x16x32_bf16 v[80:83], v[188:191], v[144:147], v[80:83]
	v_mfma_f32_16x16x32_bf16 v[84:87], v[196:199], v[144:147], v[84:87]
	v_mfma_f32_16x16x32_bf16 v[88:91], v[188:191], v[148:151], v[88:91]
	v_mfma_f32_16x16x32_bf16 v[92:95], v[196:199], v[148:151], v[92:95]
	s_waitcnt lgkmcnt(0)
	v_mfma_f32_16x16x32_bf16 v[96:99], v[188:191], v[164:167], v[96:99]
	v_mfma_f32_16x16x32_bf16 v[100:103], v[196:199], v[164:167], v[100:103]
	v_mfma_f32_16x16x32_bf16 v[104:107], v[188:191], v[168:171], v[104:107]
	v_mfma_f32_16x16x32_bf16 v[108:111], v[196:199], v[168:171], v[108:111]
	v_mfma_f32_16x16x32_bf16 v[112:115], v[188:191], v[172:175], v[112:115]
	v_mfma_f32_16x16x32_bf16 v[116:119], v[196:199], v[172:175], v[116:119]
	v_mfma_f32_16x16x32_bf16 v[120:123], v[188:191], v[176:179], v[120:123]
	v_mfma_f32_16x16x32_bf16 v[124:127], v[196:199], v[176:179], v[124:127]
	s_waitcnt vmcnt(0)
	s_barrier
	s_cmp_ge_u32 s63, 14
	s_cbranch_scc1 .Lg2_ff1_noissue16
	s_add_u32 s56, s56, 0x80
	s_addc_u32 s57, s57, 0
	s_add_u32 s58, s58, 0x80
	s_addc_u32 s59, s59, 0
	s_add_u32 s4, s56, 0x0
	s_addc_u32 s5, s57, 0
	s_add_u32 m0, s62, 0x0
	s_nop 0
	global_load_lds_dwordx4 v162, s[4:5]
	s_add_u32 s4, s56, 0x10000
	s_addc_u32 s5, s57, 0
	s_add_u32 m0, s62, 0x1000
	s_nop 0
	global_load_lds_dwordx4 v162, s[4:5]
	s_add_u32 s4, s56, 0x20000
	s_addc_u32 s5, s57, 0
	s_add_u32 m0, s62, 0x2000
	s_nop 0
	global_load_lds_dwordx4 v162, s[4:5]
	s_add_u32 s4, s56, 0x30000
	s_addc_u32 s5, s57, 0
	s_add_u32 m0, s62, 0x3000
	s_nop 0
	global_load_lds_dwordx4 v162, s[4:5]
	s_add_u32 s4, s56, 0x40000
	s_addc_u32 s5, s57, 0
	s_add_u32 m0, s62, 0x4000
	s_nop 0
	global_load_lds_dwordx4 v162, s[4:5]
	s_add_u32 s4, s56, 0x50000
	s_addc_u32 s5, s57, 0
	s_add_u32 m0, s62, 0x5000
	s_nop 0
	global_load_lds_dwordx4 v162, s[4:5]
	s_add_u32 s4, s56, 0x60000
	s_addc_u32 s5, s57, 0
	s_add_u32 m0, s62, 0x6000
	s_nop 0
	global_load_lds_dwordx4 v162, s[4:5]
	s_add_u32 s4, s56, 0x70000
	s_addc_u32 s5, s57, 0
	s_add_u32 m0, s62, 0x7000
	s_nop 0
	global_load_lds_dwordx4 v162, s[4:5]
	s_cmp_eq_u32 s65, 0
	s_cbranch_scc1 .Lg2_ff1_nodma8_4
	s_cmp_gt_u32 s70, 1
	s_cbranch_scc1 .Lg2_ff1_nodma8_4
	s_add_u32 s4, s56, 0x80000
	s_addc_u32 s5, s57, 0
	s_add_u32 m0, s62, 0x8000
	s_nop 0
	global_load_lds_dwordx4 v162, s[4:5]

.Lg2_ff1_noissue16:
	ds_read_b128 v[136:139], v158 offset:0
	ds_read_b128 v[140:143], v158 offset:2048
	ds_read_b128 v[144:147], v158 offset:4096
	ds_read_b128 v[148:151], v158 offset:6144
	ds_read_b128 v[164:167], v158 offset:8192
	ds_read_b128 v[168:171], v158 offset:10240
	ds_read_b128 v[172:175], v158 offset:12288
	ds_read_b128 v[176:179], v158 offset:14336
	s_waitcnt lgkmcnt(4)
	v_mfma_f32_16x16x32_bf16 v[0:3], v[200:203], v[136:139], v[0:3]
	v_mfma_f32_16x16x32_bf16 v[4:7], v[208:211], v[136:139], v[4:7]
	v_mfma_f32_16x16x32_bf16 v[8:11], v[200:203], v[140:143], v[8:11]
	v_mfma_f32_16x16x32_bf16 v[12:15], v[208:211], v[140:143], v[12:15]
	v_mfma_f32_16x16x32_bf16 v[16:19], v[200:203], v[144:147], v[16:19]
	v_mfma_f32_16x16x32_bf16 v[20:23], v[208:211], v[144:147], v[20:23]
	v_mfma_f32_16x16x32_bf16 v[24:27], v[200:203], v[148:151], v[24:27]
	v_mfma_f32_16x16x32_bf16 v[28:31], v[208:211], v[148:151], v[28:31]
	ds_read_b128 v[136:139], v158 offset:16384
	ds_read_b128 v[140:143], v158 offset:18432
	ds_read_b128 v[144:147], v158 offset:20480
	ds_read_b128 v[148:151], v158 offset:22528
	s_waitcnt lgkmcnt(4)
	v_mfma_f32_16x16x32_bf16 v[32:35], v[200:203], v[164:167], v[32:35]
	v_mfma_f32_16x16x32_bf16 v[36:39], v[208:211], v[164:167], v[36:39]
	v_mfma_f32_16x16x32_bf16 v[40:43], v[200:203], v[168:171], v[40:43]
	v_mfma_f32_16x16x32_bf16 v[44:47], v[208:211], v[168:171], v[44:47]
	v_mfma_f32_16x16x32_bf16 v[48:51], v[200:203], v[172:175], v[48:51]
	v_mfma_f32_16x16x32_bf16 v[52:55], v[208:211], v[172:175], v[52:55]
	v_mfma_f32_16x16x32_bf16 v[56:59], v[200:203], v[176:179], v[56:59]
	v_mfma_f32_16x16x32_bf16 v[60:63], v[208:211], v[176:179], v[60:63]
	ds_read_b128 v[164:167], v158 offset:24576
	ds_read_b128 v[168:171], v158 offset:26624
	ds_read_b128 v[172:175], v158 offset:28672
	ds_read_b128 v[176:179], v158 offset:30720
	s_waitcnt lgkmcnt(4)
	v_mfma_f32_16x16x32_bf16 v[64:67], v[200:203], v[136:139], v[64:67]
	v_mfma_f32_16x16x32_bf16 v[68:71], v[208:211], v[136:139], v[68:71]
	v_mfma_f32_16x16x32_bf16 v[72:75], v[200:203], v[140:143], v[72:75]
	v_mfma_f32_16x16x32_bf16 v[76:79], v[208:211], v[140:143], v[76:79]
	v_mfma_f32_16x16x32_bf16 v[80:83], v[200:203], v[144:147], v[80:83]
	v_mfma_f32_16x16x32_bf16 v[84:87], v[208:211], v[144:147], v[84:87]
	v_mfma_f32_16x16x32_bf16 v[88:91], v[200:203], v[148:151], v[88:91]
	v_mfma_f32_16x16x32_bf16 v[92:95], v[208:211], v[148:151], v[92:95]
	ds_read_b128 v[136:139], v159 offset:0
	ds_read_b128 v[140:143], v159 offset:2048
	ds_read_b128 v[144:147], v159 offset:4096
	ds_read_b128 v[148:151], v159 offset:6144
	s_waitcnt lgkmcnt(4)
	v_mfma_f32_16x16x32_bf16 v[96:99], v[200:203], v[164:167], v[96:99]
	v_mfma_f32_16x16x32_bf16 v[100:103], v[208:211], v[164:167], v[100:103]
	v_mfma_f32_16x16x32_bf16 v[104:107], v[200:203], v[168:171], v[104:107]
	v_mfma_f32_16x16x32_bf16 v[108:111], v[208:211], v[168:171], v[108:111]
	v_mfma_f32_16x16x32_bf16 v[112:115], v[200:203], v[172:175], v[112:115]
	v_mfma_f32_16x16x32_bf16 v[116:119], v[208:211], v[172:175], v[116:119]
	v_mfma_f32_16x16x32_bf16 v[120:123], v[200:203], v[176:179], v[120:123]
	v_mfma_f32_16x16x32_bf16 v[124:127], v[208:211], v[176:179], v[124:127]
	ds_read_b128 v[164:167], v159 offset:8192
	ds_read_b128 v[168:171], v159 offset:10240
	ds_read_b128 v[172:175], v159 offset:12288
	ds_read_b128 v[176:179], v159 offset:14336
	s_waitcnt lgkmcnt(4)
	v_mfma_f32_16x16x32_bf16 v[0:3], v[204:207], v[136:139], v[0:3]
	v_mfma_f32_16x16x32_bf16 v[4:7], v[240:243], v[136:139], v[4:7]
	v_mfma_f32_16x16x32_bf16 v[8:11], v[204:207], v[140:143], v[8:11]
	v_mfma_f32_16x16x32_bf16 v[12:15], v[240:243], v[140:143], v[12:15]
	v_mfma_f32_16x16x32_bf16 v[16:19], v[204:207], v[144:147], v[16:19]
	v_mfma_f32_16x16x32_bf16 v[20:23], v[240:243], v[144:147], v[20:23]
	v_mfma_f32_16x16x32_bf16 v[24:27], v[204:207], v[148:151], v[24:27]
	v_mfma_f32_16x16x32_bf16 v[28:31], v[240:243], v[148:151], v[28:31]
	ds_read_b128 v[136:139], v159 offset:16384
	ds_read_b128 v[140:143], v159 offset:18432
	ds_read_b128 v[144:147], v159 offset:20480
	ds_read_b128 v[148:151], v159 offset:22528
	s_waitcnt lgkmcnt(4)
	v_mfma_f32_16x16x32_bf16 v[32:35], v[204:207], v[164:167], v[32:35]
	v_mfma_f32_16x16x32_bf16 v[36:39], v[240:243], v[164:167], v[36:39]
	v_mfma_f32_16x16x32_bf16 v[40:43], v[204:207], v[168:171], v[40:43]
	v_mfma_f32_16x16x32_bf16 v[44:47], v[240:243], v[168:171], v[44:47]
	v_mfma_f32_16x16x32_bf16 v[48:51], v[204:207], v[172:175], v[48:51]
	v_mfma_f32_16x16x32_bf16 v[52:55], v[240:243], v[172:175], v[52:55]
	v_mfma_f32_16x16x32_bf16 v[56:59], v[204:207], v[176:179], v[56:59]
	v_mfma_f32_16x16x32_bf16 v[60:63], v[240:243], v[176:179], v[60:63]
	ds_read_b128 v[164:167], v159 offset:24576
	ds_read_b128 v[168:171], v159 offset:26624
	ds_read_b128 v[172:175], v159 offset:28672
	ds_read_b128 v[176:179], v159 offset:30720
	s_waitcnt lgkmcnt(4)
	v_mfma_f32_16x16x32_bf16 v[64:67], v[204:207], v[136:139], v[64:67]
	v_mfma_f32_16x16x32_bf16 v[68:71], v[240:243], v[136:139], v[68:71]
	v_mfma_f32_16x16x32_bf16 v[72:75], v[204:207], v[140:143], v[72:75]
	v_mfma_f32_16x16x32_bf16 v[76:79], v[240:243], v[140:143], v[76:79]
	v_mfma_f32_16x16x32_bf16 v[80:83], v[204:207], v[144:147], v[80:83]
	v_mfma_f32_16x16x32_bf16 v[84:87], v[240:243], v[144:147], v[84:87]
	v_mfma_f32_16x16x32_bf16 v[88:91], v[204:207], v[148:151], v[88:91]
	v_mfma_f32_16x16x32_bf16 v[92:95], v[240:243], v[148:151], v[92:95]
	s_waitcnt lgkmcnt(0)
	v_mfma_f32_16x16x32_bf16 v[96:99], v[204:207], v[164:167], v[96:99]
	v_mfma_f32_16x16x32_bf16 v[100:103], v[240:243], v[164:167], v[100:103]
	v_mfma_f32_16x16x32_bf16 v[104:107], v[204:207], v[168:171], v[104:107]
	v_mfma_f32_16x16x32_bf16 v[108:111], v[240:243], v[168:171], v[108:111]
	v_mfma_f32_16x16x32_bf16 v[112:115], v[204:207], v[172:175], v[112:115]
	v_mfma_f32_16x16x32_bf16 v[116:119], v[240:243], v[172:175], v[116:119]
	v_mfma_f32_16x16x32_bf16 v[120:123], v[204:207], v[176:179], v[120:123]
	v_mfma_f32_16x16x32_bf16 v[124:127], v[240:243], v[176:179], v[124:127]
	s_add_i32 s63, s63, 2
	s_cmp_lt_u32 s63, 16
	s_cbranch_scc1 .Lg2_ff1_loop16
.Lg2_ff1_epi:
	s_nop 7
	s_nop 7
	s_barrier
	v_add_u32_e32 v253, 0x8000, v212
	v_add_u32_e32 v254, 0x8000, v213
	v_max_f32_e32 v0, 0, v0
	v_max_f32_e32 v1, 0, v1
	v_max_f32_e32 v2, 0, v2
	v_max_f32_e32 v3, 0, v3
	v_mul_f32_e32 v0, v0, v0
	v_mul_f32_e32 v1, v1, v1
	v_mul_f32_e32 v2, v2, v2
	v_mul_f32_e32 v3, v3, v3
	v_cvt_pk_bf16_f32 v0, v0, v1
	v_cvt_pk_bf16_f32 v1, v2, v3
	ds_write_b64 v212, v[0:1] offset:0
	v_max_f32_e32 v4, 0, v4
	v_max_f32_e32 v5, 0, v5
	v_max_f32_e32 v6, 0, v6
	v_max_f32_e32 v7, 0, v7
	v_mul_f32_e32 v4, v4, v4
	v_mul_f32_e32 v5, v5, v5
	v_mul_f32_e32 v6, v6, v6
	v_mul_f32_e32 v7, v7, v7
	v_cvt_pk_bf16_f32 v4, v4, v5
	v_cvt_pk_bf16_f32 v5, v6, v7
	ds_write_b64 v213, v[4:5] offset:0
	v_max_f32_e32 v8, 0, v8
	v_max_f32_e32 v9, 0, v9
	v_max_f32_e32 v10, 0, v10
	v_max_f32_e32 v11, 0, v11
	v_mul_f32_e32 v8, v8, v8
	v_mul_f32_e32 v9, v9, v9
	v_mul_f32_e32 v10, v10, v10
	v_mul_f32_e32 v11, v11, v11
	v_cvt_pk_bf16_f32 v8, v8, v9
	v_cvt_pk_bf16_f32 v9, v10, v11
	ds_write_b64 v212, v[8:9] offset:4096
	v_max_f32_e32 v12, 0, v12
	v_max_f32_e32 v13, 0, v13
	v_max_f32_e32 v14, 0, v14
	v_max_f32_e32 v15, 0, v15
	v_mul_f32_e32 v12, v12, v12
	v_mul_f32_e32 v13, v13, v13
	v_mul_f32_e32 v14, v14, v14
	v_mul_f32_e32 v15, v15, v15
	v_cvt_pk_bf16_f32 v12, v12, v13
	v_cvt_pk_bf16_f32 v13, v14, v15
	ds_write_b64 v213, v[12:13] offset:4096
	v_max_f32_e32 v16, 0, v16
	v_max_f32_e32 v17, 0, v17
	v_max_f32_e32 v18, 0, v18
	v_max_f32_e32 v19, 0, v19
	v_mul_f32_e32 v16, v16, v16
	v_mul_f32_e32 v17, v17, v17
	v_mul_f32_e32 v18, v18, v18
	v_mul_f32_e32 v19, v19, v19
	v_cvt_pk_bf16_f32 v16, v16, v17
	v_cvt_pk_bf16_f32 v17, v18, v19
	ds_write_b64 v212, v[16:17] offset:8192
	v_max_f32_e32 v20, 0, v20
	v_max_f32_e32 v21, 0, v21
	v_max_f32_e32 v22, 0, v22
	v_max_f32_e32 v23, 0, v23
	v_mul_f32_e32 v20, v20, v20
	v_mul_f32_e32 v21, v21, v21
	v_mul_f32_e32 v22, v22, v22
	v_mul_f32_e32 v23, v23, v23
	v_cvt_pk_bf16_f32 v20, v20, v21
	v_cvt_pk_bf16_f32 v21, v22, v23
	ds_write_b64 v213, v[20:21] offset:8192
	v_max_f32_e32 v24, 0, v24
	v_max_f32_e32 v25, 0, v25
	v_max_f32_e32 v26, 0, v26
	v_max_f32_e32 v27, 0, v27
	v_mul_f32_e32 v24, v24, v24
	v_mul_f32_e32 v25, v25, v25
	v_mul_f32_e32 v26, v26, v26
	v_mul_f32_e32 v27, v27, v27
	v_cvt_pk_bf16_f32 v24, v24, v25
	v_cvt_pk_bf16_f32 v25, v26, v27
	ds_write_b64 v212, v[24:25] offset:12288
	v_max_f32_e32 v28, 0, v28
	v_max_f32_e32 v29, 0, v29
	v_max_f32_e32 v30, 0, v30
	v_max_f32_e32 v31, 0, v31
	v_mul_f32_e32 v28, v28, v28
	v_mul_f32_e32 v29, v29, v29
	v_mul_f32_e32 v30, v30, v30
	v_mul_f32_e32 v31, v31, v31
	v_cvt_pk_bf16_f32 v28, v28, v29
	v_cvt_pk_bf16_f32 v29, v30, v31
	ds_write_b64 v213, v[28:29] offset:12288
	v_max_f32_e32 v32, 0, v32
	v_max_f32_e32 v33, 0, v33
	v_max_f32_e32 v34, 0, v34
	v_max_f32_e32 v35, 0, v35
	v_mul_f32_e32 v32, v32, v32
	v_mul_f32_e32 v33, v33, v33
	v_mul_f32_e32 v34, v34, v34
	v_mul_f32_e32 v35, v35, v35
	v_cvt_pk_bf16_f32 v32, v32, v33
	v_cvt_pk_bf16_f32 v33, v34, v35
	ds_write_b64 v212, v[32:33] offset:16384
	v_max_f32_e32 v36, 0, v36
	v_max_f32_e32 v37, 0, v37
	v_max_f32_e32 v38, 0, v38
	v_max_f32_e32 v39, 0, v39
	v_mul_f32_e32 v36, v36, v36
	v_mul_f32_e32 v37, v37, v37
	v_mul_f32_e32 v38, v38, v38
	v_mul_f32_e32 v39, v39, v39
	v_cvt_pk_bf16_f32 v36, v36, v37
	v_cvt_pk_bf16_f32 v37, v38, v39
	ds_write_b64 v213, v[36:37] offset:16384
	v_max_f32_e32 v40, 0, v40
	v_max_f32_e32 v41, 0, v41
	v_max_f32_e32 v42, 0, v42
	v_max_f32_e32 v43, 0, v43
	v_mul_f32_e32 v40, v40, v40
	v_mul_f32_e32 v41, v41, v41
	v_mul_f32_e32 v42, v42, v42
	v_mul_f32_e32 v43, v43, v43
	v_cvt_pk_bf16_f32 v40, v40, v41
	v_cvt_pk_bf16_f32 v41, v42, v43
	ds_write_b64 v212, v[40:41] offset:20480
	v_max_f32_e32 v44, 0, v44
	v_max_f32_e32 v45, 0, v45
	v_max_f32_e32 v46, 0, v46
	v_max_f32_e32 v47, 0, v47
	v_mul_f32_e32 v44, v44, v44
	v_mul_f32_e32 v45, v45, v45
	v_mul_f32_e32 v46, v46, v46
	v_mul_f32_e32 v47, v47, v47
	v_cvt_pk_bf16_f32 v44, v44, v45
	v_cvt_pk_bf16_f32 v45, v46, v47
	ds_write_b64 v213, v[44:45] offset:20480
	v_max_f32_e32 v48, 0, v48
	v_max_f32_e32 v49, 0, v49
	v_max_f32_e32 v50, 0, v50
	v_max_f32_e32 v51, 0, v51
	v_mul_f32_e32 v48, v48, v48
	v_mul_f32_e32 v49, v49, v49
	v_mul_f32_e32 v50, v50, v50
	v_mul_f32_e32 v51, v51, v51
	v_cvt_pk_bf16_f32 v48, v48, v49
	v_cvt_pk_bf16_f32 v49, v50, v51
	ds_write_b64 v212, v[48:49] offset:24576
	v_max_f32_e32 v52, 0, v52
	v_max_f32_e32 v53, 0, v53
	v_max_f32_e32 v54, 0, v54
	v_max_f32_e32 v55, 0, v55
	v_mul_f32_e32 v52, v52, v52
	v_mul_f32_e32 v53, v53, v53
	v_mul_f32_e32 v54, v54, v54
	v_mul_f32_e32 v55, v55, v55
	v_cvt_pk_bf16_f32 v52, v52, v53
	v_cvt_pk_bf16_f32 v53, v54, v55
	ds_write_b64 v213, v[52:53] offset:24576
	v_max_f32_e32 v56, 0, v56
	v_max_f32_e32 v57, 0, v57
	v_max_f32_e32 v58, 0, v58
	v_max_f32_e32 v59, 0, v59
	v_mul_f32_e32 v56, v56, v56
	v_mul_f32_e32 v57, v57, v57
	v_mul_f32_e32 v58, v58, v58
	v_mul_f32_e32 v59, v59, v59
	v_cvt_pk_bf16_f32 v56, v56, v57
	v_cvt_pk_bf16_f32 v57, v58, v59
	ds_write_b64 v212, v[56:57] offset:28672
	v_max_f32_e32 v60, 0, v60
	v_max_f32_e32 v61, 0, v61
	v_max_f32_e32 v62, 0, v62
	v_max_f32_e32 v63, 0, v63
	v_mul_f32_e32 v60, v60, v60
	v_mul_f32_e32 v61, v61, v61
	v_mul_f32_e32 v62, v62, v62
	v_mul_f32_e32 v63, v63, v63
	v_cvt_pk_bf16_f32 v60, v60, v61
	v_cvt_pk_bf16_f32 v61, v62, v63
	ds_write_b64 v213, v[60:61] offset:28672
	v_max_f32_e32 v64, 0, v64
	v_max_f32_e32 v65, 0, v65
	v_max_f32_e32 v66, 0, v66
	v_max_f32_e32 v67, 0, v67
	v_mul_f32_e32 v64, v64, v64
	v_mul_f32_e32 v65, v65, v65
	v_mul_f32_e32 v66, v66, v66
	v_mul_f32_e32 v67, v67, v67
	v_cvt_pk_bf16_f32 v64, v64, v65
	v_cvt_pk_bf16_f32 v65, v66, v67
	ds_write_b64 v253, v[64:65] offset:0
	v_max_f32_e32 v68, 0, v68
	v_max_f32_e32 v69, 0, v69
	v_max_f32_e32 v70, 0, v70
	v_max_f32_e32 v71, 0, v71
	v_mul_f32_e32 v68, v68, v68
	v_mul_f32_e32 v69, v69, v69
	v_mul_f32_e32 v70, v70, v70
	v_mul_f32_e32 v71, v71, v71
	v_cvt_pk_bf16_f32 v68, v68, v69
	v_cvt_pk_bf16_f32 v69, v70, v71
	ds_write_b64 v254, v[68:69] offset:0
	v_max_f32_e32 v72, 0, v72
	v_max_f32_e32 v73, 0, v73
	v_max_f32_e32 v74, 0, v74
	v_max_f32_e32 v75, 0, v75
	v_mul_f32_e32 v72, v72, v72
	v_mul_f32_e32 v73, v73, v73
	v_mul_f32_e32 v74, v74, v74
	v_mul_f32_e32 v75, v75, v75
	v_cvt_pk_bf16_f32 v72, v72, v73
	v_cvt_pk_bf16_f32 v73, v74, v75
	ds_write_b64 v253, v[72:73] offset:4096
	v_max_f32_e32 v76, 0, v76
	v_max_f32_e32 v77, 0, v77
	v_max_f32_e32 v78, 0, v78
	v_max_f32_e32 v79, 0, v79
	v_mul_f32_e32 v76, v76, v76
	v_mul_f32_e32 v77, v77, v77
	v_mul_f32_e32 v78, v78, v78
	v_mul_f32_e32 v79, v79, v79
	v_cvt_pk_bf16_f32 v76, v76, v77
	v_cvt_pk_bf16_f32 v77, v78, v79
	ds_write_b64 v254, v[76:77] offset:4096
	v_max_f32_e32 v80, 0, v80
	v_max_f32_e32 v81, 0, v81
	v_max_f32_e32 v82, 0, v82
	v_max_f32_e32 v83, 0, v83
	v_mul_f32_e32 v80, v80, v80
	v_mul_f32_e32 v81, v81, v81
	v_mul_f32_e32 v82, v82, v82
	v_mul_f32_e32 v83, v83, v83
	v_cvt_pk_bf16_f32 v80, v80, v81
	v_cvt_pk_bf16_f32 v81, v82, v83
	ds_write_b64 v253, v[80:81] offset:8192
	v_max_f32_e32 v84, 0, v84
	v_max_f32_e32 v85, 0, v85
	v_max_f32_e32 v86, 0, v86
	v_max_f32_e32 v87, 0, v87
	v_mul_f32_e32 v84, v84, v84
	v_mul_f32_e32 v85, v85, v85
	v_mul_f32_e32 v86, v86, v86
	v_mul_f32_e32 v87, v87, v87
	v_cvt_pk_bf16_f32 v84, v84, v85
	v_cvt_pk_bf16_f32 v85, v86, v87
	ds_write_b64 v254, v[84:85] offset:8192
	v_max_f32_e32 v88, 0, v88
	v_max_f32_e32 v89, 0, v89
	v_max_f32_e32 v90, 0, v90
	v_max_f32_e32 v91, 0, v91
	v_mul_f32_e32 v88, v88, v88
	v_mul_f32_e32 v89, v89, v89
	v_mul_f32_e32 v90, v90, v90
	v_mul_f32_e32 v91, v91, v91
	v_cvt_pk_bf16_f32 v88, v88, v89
	v_cvt_pk_bf16_f32 v89, v90, v91
	ds_write_b64 v253, v[88:89] offset:12288
	v_max_f32_e32 v92, 0, v92
	v_max_f32_e32 v93, 0, v93
	v_max_f32_e32 v94, 0, v94
	v_max_f32_e32 v95, 0, v95
	v_mul_f32_e32 v92, v92, v92
	v_mul_f32_e32 v93, v93, v93
	v_mul_f32_e32 v94, v94, v94
	v_mul_f32_e32 v95, v95, v95
	v_cvt_pk_bf16_f32 v92, v92, v93
	v_cvt_pk_bf16_f32 v93, v94, v95
	ds_write_b64 v254, v[92:93] offset:12288
	v_max_f32_e32 v96, 0, v96
	v_max_f32_e32 v97, 0, v97
	v_max_f32_e32 v98, 0, v98
	v_max_f32_e32 v99, 0, v99
	v_mul_f32_e32 v96, v96, v96
	v_mul_f32_e32 v97, v97, v97
	v_mul_f32_e32 v98, v98, v98
	v_mul_f32_e32 v99, v99, v99
	v_cvt_pk_bf16_f32 v96, v96, v97
	v_cvt_pk_bf16_f32 v97, v98, v99
	ds_write_b64 v253, v[96:97] offset:16384
	v_max_f32_e32 v100, 0, v100
	v_max_f32_e32 v101, 0, v101
	v_max_f32_e32 v102, 0, v102
	v_max_f32_e32 v103, 0, v103
	v_mul_f32_e32 v100, v100, v100
	v_mul_f32_e32 v101, v101, v101
	v_mul_f32_e32 v102, v102, v102
	v_mul_f32_e32 v103, v103, v103
	v_cvt_pk_bf16_f32 v100, v100, v101
	v_cvt_pk_bf16_f32 v101, v102, v103
	ds_write_b64 v254, v[100:101] offset:16384
	v_max_f32_e32 v104, 0, v104
	v_max_f32_e32 v105, 0, v105
	v_max_f32_e32 v106, 0, v106
	v_max_f32_e32 v107, 0, v107
	v_mul_f32_e32 v104, v104, v104
	v_mul_f32_e32 v105, v105, v105
	v_mul_f32_e32 v106, v106, v106
	v_mul_f32_e32 v107, v107, v107
	v_cvt_pk_bf16_f32 v104, v104, v105
	v_cvt_pk_bf16_f32 v105, v106, v107
	ds_write_b64 v253, v[104:105] offset:20480
	v_max_f32_e32 v108, 0, v108
	v_max_f32_e32 v109, 0, v109
	v_max_f32_e32 v110, 0, v110
	v_max_f32_e32 v111, 0, v111
	v_mul_f32_e32 v108, v108, v108
	v_mul_f32_e32 v109, v109, v109
	v_mul_f32_e32 v110, v110, v110
	v_mul_f32_e32 v111, v111, v111
	v_cvt_pk_bf16_f32 v108, v108, v109
	v_cvt_pk_bf16_f32 v109, v110, v111
	ds_write_b64 v254, v[108:109] offset:20480
	v_max_f32_e32 v112, 0, v112
	v_max_f32_e32 v113, 0, v113
	v_max_f32_e32 v114, 0, v114
	v_max_f32_e32 v115, 0, v115
	v_mul_f32_e32 v112, v112, v112
	v_mul_f32_e32 v113, v113, v113
	v_mul_f32_e32 v114, v114, v114
	v_mul_f32_e32 v115, v115, v115
	v_cvt_pk_bf16_f32 v112, v112, v113
	v_cvt_pk_bf16_f32 v113, v114, v115
	ds_write_b64 v253, v[112:113] offset:24576
	v_max_f32_e32 v116, 0, v116
	v_max_f32_e32 v117, 0, v117
	v_max_f32_e32 v118, 0, v118
	v_max_f32_e32 v119, 0, v119
	v_mul_f32_e32 v116, v116, v116
	v_mul_f32_e32 v117, v117, v117
	v_mul_f32_e32 v118, v118, v118
	v_mul_f32_e32 v119, v119, v119
	v_cvt_pk_bf16_f32 v116, v116, v117
	v_cvt_pk_bf16_f32 v117, v118, v119
	ds_write_b64 v254, v[116:117] offset:24576
	v_max_f32_e32 v120, 0, v120
	v_max_f32_e32 v121, 0, v121
	v_max_f32_e32 v122, 0, v122
	v_max_f32_e32 v123, 0, v123
	v_mul_f32_e32 v120, v120, v120
	v_mul_f32_e32 v121, v121, v121
	v_mul_f32_e32 v122, v122, v122
	v_mul_f32_e32 v123, v123, v123
	v_cvt_pk_bf16_f32 v120, v120, v121
	v_cvt_pk_bf16_f32 v121, v122, v123
	ds_write_b64 v253, v[120:121] offset:28672
	v_max_f32_e32 v124, 0, v124
	v_max_f32_e32 v125, 0, v125
	v_max_f32_e32 v126, 0, v126
	v_max_f32_e32 v127, 0, v127
	v_mul_f32_e32 v124, v124, v124
	v_mul_f32_e32 v125, v125, v125
	v_mul_f32_e32 v126, v126, v126
	v_mul_f32_e32 v127, v127, v127
	v_cvt_pk_bf16_f32 v124, v124, v125
	v_cvt_pk_bf16_f32 v125, v126, v127
	ds_write_b64 v254, v[124:125] offset:28672
	s_cmp_eq_u32 s65, 0
	s_cbranch_scc1 .Lg2_ff1_st16
	v_max_f32_e32 v128, 0, v128
	v_max_f32_e32 v129, 0, v129
	v_max_f32_e32 v130, 0, v130
	v_max_f32_e32 v131, 0, v131
	v_mul_f32_e32 v128, v128, v128
	v_mul_f32_e32 v129, v129, v129
	v_mul_f32_e32 v130, v130, v130
	v_mul_f32_e32 v131, v131, v131
	v_cvt_pk_bf16_f32 v128, v128, v129
	v_cvt_pk_bf16_f32 v129, v130, v131
	ds_write_b64 v253, v[128:129] offset:32768
	v_max_f32_e32 v132, 0, v132
	v_max_f32_e32 v133, 0, v133
	v_max_f32_e32 v134, 0, v134
	v_max_f32_e32 v135, 0, v135
	v_mul_f32_e32 v132, v132, v132
	v_mul_f32_e32 v133, v133, v133
	v_mul_f32_e32 v134, v134, v134
	v_mul_f32_e32 v135, v135, v135
	v_cvt_pk_bf16_f32 v132, v132, v133
	v_cvt_pk_bf16_f32 v133, v134, v135
	ds_write_b64 v254, v[132:133] offset:32768

.Lg2_ff1_rd16a:
	s_waitcnt lgkmcnt(0)
	global_store_dwordx4 v252, v[0:3], s[60:61]
	s_add_u32 s60, s60, 0x20000
	s_addc_u32 s61, s61, 0
	global_store_dwordx4 v252, v[4:7], s[60:61]
	s_add_u32 s60, s60, 0x20000
	s_addc_u32 s61, s61, 0
	global_store_dwordx4 v252, v[8:11], s[60:61]
	s_add_u32 s60, s60, 0x20000
	s_addc_u32 s61, s61, 0
	global_store_dwordx4 v252, v[12:15], s[60:61]
	s_add_u32 s60, s60, 0x20000
	s_addc_u32 s61, s61, 0
	global_store_dwordx4 v252, v[16:19], s[60:61]
	s_add_u32 s60, s60, 0x20000
	s_addc_u32 s61, s61, 0
	global_store_dwordx4 v252, v[20:23], s[60:61]
	s_add_u32 s60, s60, 0x20000
	s_addc_u32 s61, s61, 0
	global_store_dwordx4 v252, v[24:27], s[60:61]
	s_add_u32 s60, s60, 0x20000
	s_addc_u32 s61, s61, 0
	global_store_dwordx4 v252, v[28:31], s[60:61]
	s_add_u32 s60, s60, 0x20000
	s_addc_u32 s61, s61, 0
	global_store_dwordx4 v252, v[32:35], s[60:61]
	s_add_u32 s60, s60, 0x20000
	s_addc_u32 s61, s61, 0
	global_store_dwordx4 v252, v[36:39], s[60:61]
	s_add_u32 s60, s60, 0x20000
	s_addc_u32 s61, s61, 0
	global_store_dwordx4 v252, v[40:43], s[60:61]
	s_add_u32 s60, s60, 0x20000
	s_addc_u32 s61, s61, 0
	global_store_dwordx4 v252, v[44:47], s[60:61]
	s_add_u32 s60, s60, 0x20000
	s_addc_u32 s61, s61, 0
	global_store_dwordx4 v252, v[48:51], s[60:61]
	s_add_u32 s60, s60, 0x20000
	s_addc_u32 s61, s61, 0
	global_store_dwordx4 v252, v[52:55], s[60:61]
	s_add_u32 s60, s60, 0x20000
	s_addc_u32 s61, s61, 0
	global_store_dwordx4 v252, v[56:59], s[60:61]
	s_add_u32 s60, s60, 0x20000
	s_addc_u32 s61, s61, 0
	global_store_dwordx4 v252, v[60:63], s[60:61]
	s_add_u32 s60, s60, 0x20000
	s_addc_u32 s61, s61, 0
	s_cmp_eq_u32 s65, 0
	s_cbranch_scc1 .Lg2_ff1_rd16
	global_store_dwordx4 v252, v[64:67], s[60:61]
	s_add_u32 s60, s60, 0x20000
	s_addc_u32 s61, s61, 0
.Lg2_ff1_rd16:
	s_waitcnt lgkmcnt(0)
	s_barrier
	s_add_i32 s64, s64, 1
	s_cmp_lt_u32 s64, 4
	s_cbranch_scc1 .Lg2_ff1_tile
	v_mov_b32_e32 v2, 0x10200
	v_mov_b32_e32 v4, s66
	v_mov_b32_e32 v5, s67
	ds_write_b64 v2, v[4:5]
	v_mov_b32_e32 v1, 0
	s_waitcnt vmcnt(0) lgkmcnt(0)

.Lg2_out_entry:
	s_waitcnt vmcnt(0) lgkmcnt(0)
	s_barrier
	v_mov_b32_e32 v2, 0x10200
	ds_read_b64 v[2:3], v2
	v_readlane_b32 s0, v246, 0
	v_lshrrev_b32_e32 v4, 6, v163
	v_and_b32_e32 v5, 63, v163
	s_and_b32 s1, s0, 7
	s_lshr_b32 s0, s0, 3
	s_and_b32 s68, s0, 7
	s_lshr_b32 s0, s0, 3
	s_lshl_b32 s0, s0, 3
	s_add_i32 s0, s0, s1
	s_cmp_lt_u32 s0, 32
	s_cselect_b32 s65, 1, 0
	s_min_u32 s1, s0, 32
	s_lshl_b32 s0, s0, 4
	s_add_i32 s0, s0, s1
	s_lshl_b32 s69, s0, 4
	v_readfirstlane_b32 s70, v4
	v_and_b32_e32 v6, 15, v5
	v_lshrrev_b32_e32 v7, 4, v5
	s_waitcnt lgkmcnt(0)
	v_readfirstlane_b32 s66, v2
	v_readfirstlane_b32 s67, v3
	s_lshl_b32 s62, s70, 10
	v_and_b32_e32 v8, 7, v6
	v_xor_b32_e32 v9, v7, v8
	v_lshlrev_b32_e32 v9, 4, v9
	v_lshl_add_u32 v156, v6, 7, v9
	v_add_u32_e32 v10, 4, v7
	v_xor_b32_e32 v10, v10, v8
	v_lshlrev_b32_e32 v10, 4, v10
	v_lshl_add_u32 v157, v6, 7, v10
	v_add_u32_e32 v158, 0x8800, v156
	v_add_u32_e32 v159, 0x8800, v157
	v_lshl_add_u32 v11, v4, 5, v6
	s_mov_b32 s2, 0x800
	v_mul_lo_u32 v11, v11, s2
	v_lshl_add_u32 v160, v7, 4, v11
	v_add_u32_e32 v161, 0x8000, v160
	v_lshrrev_b32_e32 v11, 3, v163
	v_and_b32_e32 v12, 7, v163
	v_and_b32_e32 v13, 7, v11
	v_xor_b32_e32 v12, v12, v13
	v_lshlrev_b32_e32 v12, 4, v12
	s_mov_b32 s2, 0x800
	v_mul_lo_u32 v11, v11, s2
	v_add_u32_e32 v162, v11, v12
	v_lshrrev_b32_e32 v11, 1, v7
	v_lshl_add_u32 v11, v4, 2, v11
	v_xor_b32_e32 v12, v11, v6
	v_lshlrev_b32_e32 v12, 4, v12
	v_and_b32_e32 v13, 1, v7
	v_lshlrev_b32_e32 v13, 3, v13
	v_lshl_add_u32 v14, v6, 8, v13
	v_add_u32_e32 v212, v14, v12
	v_add_u32_e32 v11, 2, v11
	v_xor_b32_e32 v12, v11, v6
	v_lshlrev_b32_e32 v12, 4, v12
	v_add_u32_e32 v213, v14, v12
	v_lshrrev_b32_e32 v11, 4, v163
	v_and_b32_e32 v12, 15, v163
	v_xor_b32_e32 v13, v12, v11
	v_lshlrev_b32_e32 v13, 4, v13
	v_lshl_add_u32 v247, v11, 8, v13
	s_mov_b32 s2, 0x800
	v_mul_lo_u32 v11, v11, s2
	v_lshl_add_u32 v252, v12, 4, v11
	s_mov_b32 s64, 0
.Lg2_out_tile:
	s_lshl_b32 s0, s64, 3
	s_add_i32 s0, s0, s68
	s_lshl_b32 s0, s0, 7
	s_mul_i32 s2, s69, 0x800
	s_mul_hi_u32 s3, s69, 0x800
	s_add_u32 s56, s26, s2
	s_addc_u32 s57, s27, s3
	s_add_u32 s56, s56, 0x13240000
	s_addc_u32 s57, s57, 0
	s_mul_i32 s2, s0, 0x800
	s_mul_hi_u32 s3, s0, 0x800
	s_add_u32 s58, s26, s2
	s_addc_u32 s59, s27, s3
	s_add_u32 s58, s58, 0xfd40000
	s_addc_u32 s59, s59, 0
	s_mul_i32 s2, s69, 0x800
	s_mul_hi_u32 s3, s69, 0x800
	s_lshl_b32 s0, s0, 1
	s_add_u32 s2, s2, s0
	s_addc_u32 s3, s3, 0
	s_add_u32 s60, s26, s2
	s_addc_u32 s61, s27, s3
	s_add_u32 s60, s60, 0x11140000
	s_addc_u32 s61, s61, 0
	v_mov_b32_e32 v0, 0
	v_mov_b32_e32 v1, 0
	v_mov_b32_e32 v2, 0
	v_mov_b32_e32 v3, 0
	v_mov_b32_e32 v4, 0
	v_mov_b32_e32 v5, 0
	v_mov_b32_e32 v6, 0
	v_mov_b32_e32 v7, 0
	v_mov_b32_e32 v8, 0
	v_mov_b32_e32 v9, 0
	v_mov_b32_e32 v10, 0
	v_mov_b32_e32 v11, 0
	v_mov_b32_e32 v12, 0
	v_mov_b32_e32 v13, 0
	v_mov_b32_e32 v14, 0
	v_mov_b32_e32 v15, 0
	v_mov_b32_e32 v16, 0
	v_mov_b32_e32 v17, 0
	v_mov_b32_e32 v18, 0
	v_mov_b32_e32 v19, 0
	v_mov_b32_e32 v20, 0
	v_mov_b32_e32 v21, 0
	v_mov_b32_e32 v22, 0
	v_mov_b32_e32 v23, 0
	v_mov_b32_e32 v24, 0
	v_mov_b32_e32 v25, 0
	v_mov_b32_e32 v26, 0
	v_mov_b32_e32 v27, 0
	v_mov_b32_e32 v28, 0
	v_mov_b32_e32 v29, 0
	v_mov_b32_e32 v30, 0
	v_mov_b32_e32 v31, 0
	v_mov_b32_e32 v32, 0
	v_mov_b32_e32 v33, 0
	v_mov_b32_e32 v34, 0
	v_mov_b32_e32 v35, 0
	v_mov_b32_e32 v36, 0
	v_mov_b32_e32 v37, 0
	v_mov_b32_e32 v38, 0
	v_mov_b32_e32 v39, 0
	v_mov_b32_e32 v40, 0
	v_mov_b32_e32 v41, 0
	v_mov_b32_e32 v42, 0
	v_mov_b32_e32 v43, 0
	v_mov_b32_e32 v44, 0
	v_mov_b32_e32 v45, 0
	v_mov_b32_e32 v46, 0
	v_mov_b32_e32 v47, 0
	v_mov_b32_e32 v48, 0
	v_mov_b32_e32 v49, 0
	v_mov_b32_e32 v50, 0
	v_mov_b32_e32 v51, 0
	v_mov_b32_e32 v52, 0
	v_mov_b32_e32 v53, 0
	v_mov_b32_e32 v54, 0
	v_mov_b32_e32 v55, 0
	v_mov_b32_e32 v56, 0
	v_mov_b32_e32 v57, 0
	v_mov_b32_e32 v58, 0
	v_mov_b32_e32 v59, 0
	v_mov_b32_e32 v60, 0
	v_mov_b32_e32 v61, 0
	v_mov_b32_e32 v62, 0
	v_mov_b32_e32 v63, 0
	v_mov_b32_e32 v64, 0
	v_mov_b32_e32 v65, 0
	v_mov_b32_e32 v66, 0
	v_mov_b32_e32 v67, 0
	v_mov_b32_e32 v68, 0
	v_mov_b32_e32 v69, 0
	v_mov_b32_e32 v70, 0
	v_mov_b32_e32 v71, 0
	v_mov_b32_e32 v72, 0
	v_mov_b32_e32 v73, 0
	v_mov_b32_e32 v74, 0
	v_mov_b32_e32 v75, 0
	v_mov_b32_e32 v76, 0
	v_mov_b32_e32 v77, 0
	v_mov_b32_e32 v78, 0
	v_mov_b32_e32 v79, 0
	v_mov_b32_e32 v80, 0
	v_mov_b32_e32 v81, 0
	v_mov_b32_e32 v82, 0
	v_mov_b32_e32 v83, 0
	v_mov_b32_e32 v84, 0
	v_mov_b32_e32 v85, 0
	v_mov_b32_e32 v86, 0
	v_mov_b32_e32 v87, 0
	v_mov_b32_e32 v88, 0
	v_mov_b32_e32 v89, 0
	v_mov_b32_e32 v90, 0
	v_mov_b32_e32 v91, 0
	v_mov_b32_e32 v92, 0
	v_mov_b32_e32 v93, 0
	v_mov_b32_e32 v94, 0
	v_mov_b32_e32 v95, 0
	v_mov_b32_e32 v96, 0
	v_mov_b32_e32 v97, 0
	v_mov_b32_e32 v98, 0
	v_mov_b32_e32 v99, 0
	v_mov_b32_e32 v100, 0
	v_mov_b32_e32 v101, 0
	v_mov_b32_e32 v102, 0
	v_mov_b32_e32 v103, 0
	v_mov_b32_e32 v104, 0
	v_mov_b32_e32 v105, 0
	v_mov_b32_e32 v106, 0
	v_mov_b32_e32 v107, 0
	v_mov_b32_e32 v108, 0
	v_mov_b32_e32 v109, 0
	v_mov_b32_e32 v110, 0
	v_mov_b32_e32 v111, 0
	v_mov_b32_e32 v112, 0
	v_mov_b32_e32 v113, 0
	v_mov_b32_e32 v114, 0
	v_mov_b32_e32 v115, 0
	v_mov_b32_e32 v116, 0
	v_mov_b32_e32 v117, 0
	v_mov_b32_e32 v118, 0
	v_mov_b32_e32 v119, 0
	v_mov_b32_e32 v120, 0
	v_mov_b32_e32 v121, 0
	v_mov_b32_e32 v122, 0
	v_mov_b32_e32 v123, 0
	v_mov_b32_e32 v124, 0
	v_mov_b32_e32 v125, 0
	v_mov_b32_e32 v126, 0
	v_mov_b32_e32 v127, 0
	v_mov_b32_e32 v128, 0
	v_mov_b32_e32 v129, 0
	v_mov_b32_e32 v130, 0
	v_mov_b32_e32 v131, 0
	v_mov_b32_e32 v132, 0
	v_mov_b32_e32 v133, 0
	v_mov_b32_e32 v134, 0
	v_mov_b32_e32 v135, 0
	s_add_u32 s4, s56, 0x0
	s_addc_u32 s5, s57, 0
	s_add_u32 m0, s62, 0x0
	s_nop 0
	global_load_lds_dwordx4 v162, s[4:5]
	s_add_u32 s4, s56, 0x10000
	s_addc_u32 s5, s57, 0
	s_add_u32 m0, s62, 0x1000
	s_nop 0
	global_load_lds_dwordx4 v162, s[4:5]
	s_add_u32 s4, s56, 0x20000
	s_addc_u32 s5, s57, 0
	s_add_u32 m0, s62, 0x2000
	s_nop 0
	global_load_lds_dwordx4 v162, s[4:5]
	s_add_u32 s4, s56, 0x30000
	s_addc_u32 s5, s57, 0
	s_add_u32 m0, s62, 0x3000
	s_nop 0
	global_load_lds_dwordx4 v162, s[4:5]
	s_add_u32 s4, s56, 0x40000
	s_addc_u32 s5, s57, 0
	s_add_u32 m0, s62, 0x4000
	s_nop 0
	global_load_lds_dwordx4 v162, s[4:5]
	s_add_u32 s4, s56, 0x50000
	s_addc_u32 s5, s57, 0
	s_add_u32 m0, s62, 0x5000
	s_nop 0
	global_load_lds_dwordx4 v162, s[4:5]
	s_add_u32 s4, s56, 0x60000
	s_addc_u32 s5, s57, 0
	s_add_u32 m0, s62, 0x6000
	s_nop 0
	global_load_lds_dwordx4 v162, s[4:5]
	s_add_u32 s4, s56, 0x70000
	s_addc_u32 s5, s57, 0
	s_add_u32 m0, s62, 0x7000
	s_nop 0
	global_load_lds_dwordx4 v162, s[4:5]
	s_cmp_eq_u32 s65, 0
	s_cbranch_scc1 .Lg2_out_nodma8_0
	s_cmp_gt_u32 s70, 1
	s_cbranch_scc1 .Lg2_out_nodma8_0
	s_add_u32 s4, s56, 0x80000
	s_addc_u32 s5, s57, 0
	s_add_u32 m0, s62, 0x8000
	s_nop 0
	global_load_lds_dwordx4 v162, s[4:5]

.Lmla_x_pro:
	s_waitcnt vmcnt(0)
	ds_write_b128 v168, v[56:59] offset:20480
	ds_write_b128 v168, v[60:63] offset:22528
	ds_write_b128 v169, v[52:55] offset:28672
	v_lshl_add_u64 v[164:165], s[26:27], 0, v[164:165]
	v_lshl_add_u64 v[160:161], s[26:27], 0, v[160:161]
	s_mov_b64 s[0:1], 0x14b40000
	v_lshl_add_u64 v[164:165], v[164:165], 0, s[0:1]
	s_mov_b64 s[0:1], 0x1cb800
	v_lshl_add_u64 v[160:161], v[160:161], 0, s[0:1]
	s_mov_b64 s[0:1], 0x10000
	v_lshl_add_u64 v[212:213], v[164:165], 0, s[0:1]
	global_load_dwordx4 v[56:59], v[164:165], off
	global_load_dwordx4 v[60:63], v[212:213], off
	global_load_dwordx4 v[52:55], v[160:161], off
	s_mov_b64 s[0:1], 0xe4000
	v_lshl_add_u64 v[160:161], v[160:161], 0, s[0:1]
	ds_read_b128 v[4:7], v175 offset:0
	ds_read_b128 v[12:15], v175 offset:4096
	ds_read_b128 v[20:23], v175 offset:8192
	s_waitcnt lgkmcnt(0)
	v_mfma_f32_16x16x32_bf16 v[116:119], v[4:7], v[8:11], v[108:111]
	v_mfma_f32_16x16x32_bf16 v[132:135], v[4:7], v[40:43], v[112:115]
	v_mfma_f32_16x16x32_bf16 v[116:119], v[12:15], v[32:35], v[116:119]
	v_mfma_f32_16x16x32_bf16 v[132:135], v[12:15], v[44:47], v[132:135]
	v_mfma_f32_16x16x32_bf16 v[116:119], v[20:23], v[36:39], v[116:119]
	v_mfma_f32_16x16x32_bf16 v[132:135], v[20:23], v[16:19], v[132:135]
	ds_read_b128 v[4:7], v175 offset:1024
	ds_read_b128 v[12:15], v175 offset:5120
	ds_read_b128 v[20:23], v175 offset:9216
	s_waitcnt lgkmcnt(0)
	v_mfma_f32_16x16x32_bf16 v[120:123], v[4:7], v[8:11], v[108:111]
	v_mfma_f32_16x16x32_bf16 v[136:139], v[4:7], v[40:43], v[112:115]
	v_mfma_f32_16x16x32_bf16 v[120:123], v[12:15], v[32:35], v[120:123]
	v_mfma_f32_16x16x32_bf16 v[136:139], v[12:15], v[44:47], v[136:139]
	v_mfma_f32_16x16x32_bf16 v[120:123], v[20:23], v[36:39], v[120:123]
	v_mfma_f32_16x16x32_bf16 v[136:139], v[20:23], v[16:19], v[136:139]
	ds_read_b128 v[4:7], v175 offset:2048
	ds_read_b128 v[12:15], v175 offset:6144
	ds_read_b128 v[20:23], v175 offset:10240
	s_waitcnt lgkmcnt(0)
	v_mfma_f32_16x16x32_bf16 v[124:127], v[4:7], v[8:11], v[108:111]
	v_mfma_f32_16x16x32_bf16 v[140:143], v[4:7], v[40:43], v[112:115]
	v_mfma_f32_16x16x32_bf16 v[124:127], v[12:15], v[32:35], v[124:127]
	v_mfma_f32_16x16x32_bf16 v[140:143], v[12:15], v[44:47], v[140:143]
	v_mfma_f32_16x16x32_bf16 v[124:127], v[20:23], v[36:39], v[124:127]
	v_mfma_f32_16x16x32_bf16 v[140:143], v[20:23], v[16:19], v[140:143]
	ds_read_b128 v[4:7], v175 offset:3072
	ds_read_b128 v[12:15], v175 offset:7168
	ds_read_b128 v[20:23], v175 offset:11264
	s_waitcnt lgkmcnt(0)
	v_mfma_f32_16x16x32_bf16 v[128:131], v[4:7], v[8:11], v[108:111]
	v_mfma_f32_16x16x32_bf16 v[144:147], v[4:7], v[40:43], v[112:115]
	v_mfma_f32_16x16x32_bf16 v[128:131], v[12:15], v[32:35], v[128:131]
	v_mfma_f32_16x16x32_bf16 v[144:147], v[12:15], v[44:47], v[144:147]
	v_mfma_f32_16x16x32_bf16 v[128:131], v[20:23], v[36:39], v[128:131]
	v_mfma_f32_16x16x32_bf16 v[144:147], v[20:23], v[16:19], v[144:147]
	s_nop 7
	v_max3_f32 v2, v116, v117, v118
	v_max3_f32 v3, v132, v133, v134
	v_max3_f32 v2, v2, v119, v120
	v_max3_f32 v3, v3, v135, v136
	v_max3_f32 v2, v2, v121, v122
	v_max3_f32 v3, v3, v137, v138
	v_max3_f32 v2, v2, v123, v124
	v_max3_f32 v3, v3, v139, v140
	v_max3_f32 v2, v2, v125, v126
	v_max3_f32 v3, v3, v141, v142
	v_max3_f32 v2, v2, v127, v128
	v_max3_f32 v3, v3, v143, v144
	v_max3_f32 v2, v2, v129, v130
	v_max3_f32 v3, v3, v145, v146
	v_max3_f32 v2, v2, v131, v131
	v_max3_f32 v3, v3, v147, v147
	s_waitcnt lgkmcnt(0)
	s_barrier
.Lmla_x_body0:
	ds_read_b128 v[4:7], v175 offset:20480
	ds_read_b128 v[12:15], v175 offset:24576
	ds_read_b128 v[20:23], v175 offset:28672
	ds_read_b64_tr_b16 v[24:25], v167 offset:12288
	ds_read_b64_tr_b16 v[26:27], v167 offset:14336
	ds_read_b64_tr_b16 v[28:29], v171 offset:12288
	ds_read_b64_tr_b16 v[30:31], v171 offset:14336
	ds_read_b64_tr_b16 v[148:149], v172 offset:12288
	ds_read_b64_tr_b16 v[150:151], v172 offset:14336
	ds_read_b64_tr_b16 v[152:153], v173 offset:12288
	ds_read_b64_tr_b16 v[154:155], v173 offset:14336
	v_cmp_lt_f32_e32 vcc, s77, v2
	v_cmp_lt_f32_e64 s[2:3], s77, v3
	s_cmp_eq_u32 s57, 0
	s_cselect_b64 s[0:1], -1, 0
	s_or_b64 s[2:3], s[2:3], vcc
	s_or_b64 s[2:3], s[2:3], s[0:1]
	s_cbranch_scc1 .Lmla_x_rare0
.Lmla_x_cont0:
	v_exp_f32_e32 v116, v116
	v_exp_f32_e32 v117, v117
	v_exp_f32_e32 v118, v118
	v_exp_f32_e32 v119, v119
	v_exp_f32_e32 v132, v132
	v_exp_f32_e32 v133, v133
	v_exp_f32_e32 v134, v134
	v_exp_f32_e32 v135, v135
	s_waitcnt lgkmcnt(8)
	v_exp_f32_e32 v120, v120
	v_mfma_f32_16x16x32_bf16 v[176:179], v[4:7], v[8:11], v[108:111]
	v_exp_f32_e32 v121, v121
	v_mfma_f32_16x16x32_bf16 v[192:195], v[4:7], v[40:43], v[112:115]
	v_exp_f32_e32 v122, v122
	v_mfma_f32_16x16x32_bf16 v[176:179], v[12:15], v[32:35], v[176:179]
	v_exp_f32_e32 v123, v123
	v_mfma_f32_16x16x32_bf16 v[192:195], v[12:15], v[44:47], v[192:195]
	v_exp_f32_e32 v136, v136
	v_mfma_f32_16x16x32_bf16 v[176:179], v[20:23], v[36:39], v[176:179]
	v_exp_f32_e32 v137, v137
	v_mfma_f32_16x16x32_bf16 v[192:195], v[20:23], v[16:19], v[192:195]
	v_exp_f32_e32 v138, v138
	v_exp_f32_e32 v139, v139
	ds_read_b128 v[4:7], v175 offset:21504
	ds_read_b128 v[12:15], v175 offset:25600
	ds_read_b128 v[20:23], v175 offset:29696
	v_cvt_pk_bf16_f32 v116, v116, v117
	v_cvt_pk_bf16_f32 v117, v118, v119
	v_cvt_pk_bf16_f32 v118, v120, v121
	v_cvt_pk_bf16_f32 v119, v122, v123
	v_cvt_pk_bf16_f32 v132, v132, v133
	v_cvt_pk_bf16_f32 v133, v134, v135
	v_cvt_pk_bf16_f32 v134, v136, v137
	v_cvt_pk_bf16_f32 v135, v138, v139
	s_waitcnt lgkmcnt(0)
	v_exp_f32_e32 v124, v124
	v_mfma_f32_16x16x32_bf16 v[180:183], v[4:7], v[8:11], v[108:111]
	v_exp_f32_e32 v125, v125
	v_mfma_f32_16x16x32_bf16 v[196:199], v[4:7], v[40:43], v[112:115]
	v_exp_f32_e32 v126, v126
	v_mfma_f32_16x16x32_bf16 v[180:183], v[12:15], v[32:35], v[180:183]
	v_exp_f32_e32 v127, v127
	v_mfma_f32_16x16x32_bf16 v[196:199], v[12:15], v[44:47], v[196:199]
	v_exp_f32_e32 v140, v140
	v_mfma_f32_16x16x32_bf16 v[180:183], v[20:23], v[36:39], v[180:183]
	v_exp_f32_e32 v141, v141
	v_mfma_f32_16x16x32_bf16 v[196:199], v[20:23], v[16:19], v[196:199]
	v_exp_f32_e32 v142, v142
	v_exp_f32_e32 v143, v143
	ds_read_b128 v[4:7], v175 offset:22528
	ds_read_b128 v[12:15], v175 offset:26624
	ds_read_b128 v[20:23], v175 offset:30720
	ds_read_b64_tr_b16 v[208:209], v167 offset:16384
	ds_read_b64_tr_b16 v[210:211], v167 offset:18432
	ds_read_b64_tr_b16 v[240:241], v171 offset:16384
	ds_read_b64_tr_b16 v[242:243], v171 offset:18432
	ds_read_b64_tr_b16 v[252:253], v172 offset:16384
	ds_read_b64_tr_b16 v[254:255], v172 offset:18432
	v_mfma_f32_16x16x32_bf16 v[104:107], v[248:251], v[116:119], v[104:107]
	v_exp_f32_e32 v128, v128
	v_mfma_f32_16x16x32_bf16 v[88:91], v[248:251], v[132:135], v[88:91]
	v_exp_f32_e32 v129, v129
	v_mfma_f32_16x16x32_bf16 v[100:103], v[24:27], v[116:119], v[100:103]
	v_exp_f32_e32 v130, v130
	v_mfma_f32_16x16x32_bf16 v[80:83], v[24:27], v[132:135], v[80:83]
	v_exp_f32_e32 v131, v131
	v_mfma_f32_16x16x32_bf16 v[96:99], v[28:31], v[116:119], v[96:99]
	v_exp_f32_e32 v144, v144
	v_mfma_f32_16x16x32_bf16 v[76:79], v[28:31], v[132:135], v[76:79]
	v_exp_f32_e32 v145, v145
	s_waitcnt lgkmcnt(6)
	v_mfma_f32_16x16x32_bf16 v[184:187], v[4:7], v[8:11], v[108:111]
	v_exp_f32_e32 v146, v146
	v_exp_f32_e32 v147, v147
	v_mfma_f32_16x16x32_bf16 v[200:203], v[4:7], v[40:43], v[112:115]
	s_nop 0
	v_cvt_pk_bf16_f32 v124, v124, v125
	v_mfma_f32_16x16x32_bf16 v[184:187], v[12:15], v[32:35], v[184:187]
	v_cvt_pk_bf16_f32 v125, v126, v127
	v_cvt_pk_bf16_f32 v126, v128, v129
	v_mfma_f32_16x16x32_bf16 v[200:203], v[12:15], v[44:47], v[200:203]
	v_cvt_pk_bf16_f32 v127, v130, v131
	v_cvt_pk_bf16_f32 v140, v140, v141
	v_mfma_f32_16x16x32_bf16 v[184:187], v[20:23], v[36:39], v[184:187]
	v_cvt_pk_bf16_f32 v141, v142, v143
	v_cvt_pk_bf16_f32 v142, v144, v145
	v_mfma_f32_16x16x32_bf16 v[200:203], v[20:23], v[16:19], v[200:203]
	v_cvt_pk_bf16_f32 v143, v146, v147
	ds_read_b128 v[4:7], v175 offset:23552
	ds_read_b128 v[12:15], v175 offset:27648
	ds_read_b128 v[20:23], v175 offset:31744
	ds_read_b64_tr_b16 v[24:25], v173 offset:16384
	ds_read_b64_tr_b16 v[26:27], v173 offset:18432
	v_mfma_f32_16x16x32_bf16 v[92:95], v[148:151], v[116:119], v[92:95]
	v_mfma_f32_16x16x32_bf16 v[72:75], v[148:151], v[132:135], v[72:75]
	v_mfma_f32_16x16x32_bf16 v[84:87], v[152:155], v[116:119], v[84:87]
	v_mfma_f32_16x16x32_bf16 v[68:71], v[152:155], v[132:135], v[68:71]
	s_waitcnt lgkmcnt(2)
	v_mfma_f32_16x16x32_bf16 v[188:191], v[4:7], v[8:11], v[108:111]
	s_waitcnt vmcnt(0)
	v_mfma_f32_16x16x32_bf16 v[204:207], v[4:7], v[40:43], v[112:115]
	ds_write_b128 v168, v[56:59] offset:0
	v_mfma_f32_16x16x32_bf16 v[188:191], v[12:15], v[32:35], v[188:191]
	ds_write_b128 v168, v[60:63] offset:2048
	v_mfma_f32_16x16x32_bf16 v[204:207], v[12:15], v[44:47], v[204:207]
	ds_write_b128 v169, v[52:55] offset:8192
	v_mfma_f32_16x16x32_bf16 v[188:191], v[20:23], v[36:39], v[188:191]
	ds_write_b128 v170, v[48:51] offset:32768
	v_mfma_f32_16x16x32_bf16 v[204:207], v[20:23], v[16:19], v[204:207]
	ds_write_b128 v170, v[64:67] offset:36864
	v_mfma_f32_16x16x32_bf16 v[104:107], v[248:251], v[124:127], v[104:107]
	global_load_dwordx4 v[48:51], v[164:165], off offset:128
	s_mov_b64 s[0:1], 0x10000
	v_lshl_add_u64 v[212:213], v[164:165], 0, s[0:1]
	global_load_dwordx4 v[64:67], v[212:213], off offset:128
	v_mfma_f32_16x16x32_bf16 v[88:91], v[248:251], v[140:143], v[88:91]
	s_mov_b64 s[0:1], 0x20000
	v_lshl_add_u64 v[164:165], v[164:165], 0, s[0:1]
	global_load_dwordx4 v[56:59], v[164:165], off
	s_mov_b64 s[0:1], 0x10000
	v_mfma_f32_16x16x32_bf16 v[100:103], v[208:211], v[124:127], v[100:103]
	v_lshl_add_u64 v[212:213], v[164:165], 0, s[0:1]
	global_load_dwordx4 v[60:63], v[212:213], off
	global_load_dwordx4 v[52:55], v[160:161], off
	s_mov_b64 s[0:1], 0xe4000
	v_mfma_f32_16x16x32_bf16 v[80:83], v[208:211], v[140:143], v[80:83]
	v_lshl_add_u64 v[160:161], v[160:161], 0, s[0:1]
	v_max3_f32 v2, v176, v177, v178
	v_max3_f32 v3, v192, v193, v194
	v_max3_f32 v2, v2, v179, v180
	v_mfma_f32_16x16x32_bf16 v[96:99], v[240:243], v[124:127], v[96:99]
	v_max3_f32 v3, v3, v195, v196
	v_max3_f32 v2, v2, v181, v182
	v_max3_f32 v3, v3, v197, v198
	v_max3_f32 v2, v2, v183, v184
	v_mfma_f32_16x16x32_bf16 v[76:79], v[240:243], v[140:143], v[76:79]
	v_max3_f32 v3, v3, v199, v200
	v_max3_f32 v2, v2, v185, v186
	v_max3_f32 v3, v3, v201, v202
	v_max3_f32 v2, v2, v187, v188
	v_mfma_f32_16x16x32_bf16 v[92:95], v[252:255], v[124:127], v[92:95]
	v_max3_f32 v3, v3, v203, v204
	v_max3_f32 v2, v2, v189, v190
	v_max3_f32 v3, v3, v205, v206
	v_max3_f32 v2, v2, v191, v191
	v_mfma_f32_16x16x32_bf16 v[72:75], v[252:255], v[140:143], v[72:75]
	v_max3_f32 v3, v3, v207, v207
	s_waitcnt lgkmcnt(0)
	v_mfma_f32_16x16x32_bf16 v[84:87], v[24:27], v[124:127], v[84:87]
	v_mfma_f32_16x16x32_bf16 v[68:71], v[24:27], v[140:143], v[68:71]
	s_add_i32 s57, s57, 1
	s_cmp_lt_u32 s57, s44
	s_barrier
	s_cbranch_scc0 .Lmla_x_done
.Lmla_x_body1:
	ds_read_b128 v[4:7], v175 offset:0
	ds_read_b128 v[12:15], v175 offset:4096
	ds_read_b128 v[20:23], v175 offset:8192
	ds_read_b64_tr_b16 v[24:25], v167 offset:32768
	ds_read_b64_tr_b16 v[26:27], v167 offset:34816
	ds_read_b64_tr_b16 v[28:29], v171 offset:32768
	ds_read_b64_tr_b16 v[30:31], v171 offset:34816
	ds_read_b64_tr_b16 v[148:149], v172 offset:32768
	ds_read_b64_tr_b16 v[150:151], v172 offset:34816
	ds_read_b64_tr_b16 v[152:153], v173 offset:32768
	ds_read_b64_tr_b16 v[154:155], v173 offset:34816
	v_cmp_lt_f32_e32 vcc, s77, v2
	v_cmp_lt_f32_e64 s[2:3], s77, v3
	s_cmp_eq_u32 s57, 0
	s_cselect_b64 s[0:1], -1, 0
	s_or_b64 s[2:3], s[2:3], vcc
	s_or_b64 s[2:3], s[2:3], s[0:1]
	s_cbranch_scc1 .Lmla_x_rare1
.Lmla_x_cont1:
	v_exp_f32_e32 v176, v176
	v_exp_f32_e32 v177, v177
	v_exp_f32_e32 v178, v178
	v_exp_f32_e32 v179, v179
	v_exp_f32_e32 v192, v192
	v_exp_f32_e32 v193, v193
	v_exp_f32_e32 v194, v194
	v_exp_f32_e32 v195, v195
	s_waitcnt lgkmcnt(8)
	v_exp_f32_e32 v180, v180
	v_mfma_f32_16x16x32_bf16 v[116:119], v[4:7], v[8:11], v[108:111]
	v_exp_f32_e32 v181, v181
	v_mfma_f32_16x16x32_bf16 v[132:135], v[4:7], v[40:43], v[112:115]
	v_exp_f32_e32 v182, v182
	v_mfma_f32_16x16x32_bf16 v[116:119], v[12:15], v[32:35], v[116:119]
	v_exp_f32_e32 v183, v183
	v_mfma_f32_16x16x32_bf16 v[132:135], v[12:15], v[44:47], v[132:135]
	v_exp_f32_e32 v196, v196
	v_mfma_f32_16x16x32_bf16 v[116:119], v[20:23], v[36:39], v[116:119]
	v_exp_f32_e32 v197, v197
	v_mfma_f32_16x16x32_bf16 v[132:135], v[20:23], v[16:19], v[132:135]
	v_exp_f32_e32 v198, v198
	v_exp_f32_e32 v199, v199
	ds_read_b128 v[4:7], v175 offset:1024
	ds_read_b128 v[12:15], v175 offset:5120
	ds_read_b128 v[20:23], v175 offset:9216
	v_cvt_pk_bf16_f32 v176, v176, v177
	v_cvt_pk_bf16_f32 v177, v178, v179
	v_cvt_pk_bf16_f32 v178, v180, v181
	v_cvt_pk_bf16_f32 v179, v182, v183
	v_cvt_pk_bf16_f32 v192, v192, v193
	v_cvt_pk_bf16_f32 v193, v194, v195
	v_cvt_pk_bf16_f32 v194, v196, v197
	v_cvt_pk_bf16_f32 v195, v198, v199
	s_waitcnt lgkmcnt(0)
	v_exp_f32_e32 v184, v184
	v_mfma_f32_16x16x32_bf16 v[120:123], v[4:7], v[8:11], v[108:111]
	v_exp_f32_e32 v185, v185
	v_mfma_f32_16x16x32_bf16 v[136:139], v[4:7], v[40:43], v[112:115]
	v_exp_f32_e32 v186, v186
	v_mfma_f32_16x16x32_bf16 v[120:123], v[12:15], v[32:35], v[120:123]
	v_exp_f32_e32 v187, v187
	v_mfma_f32_16x16x32_bf16 v[136:139], v[12:15], v[44:47], v[136:139]
	v_exp_f32_e32 v200, v200
	v_mfma_f32_16x16x32_bf16 v[120:123], v[20:23], v[36:39], v[120:123]
	v_exp_f32_e32 v201, v201
	v_mfma_f32_16x16x32_bf16 v[136:139], v[20:23], v[16:19], v[136:139]
	v_exp_f32_e32 v202, v202
	v_exp_f32_e32 v203, v203
	ds_read_b128 v[4:7], v175 offset:2048
	ds_read_b128 v[12:15], v175 offset:6144
	ds_read_b128 v[20:23], v175 offset:10240
	ds_read_b64_tr_b16 v[208:209], v167 offset:36864
	ds_read_b64_tr_b16 v[210:211], v167 offset:38912
	ds_read_b64_tr_b16 v[240:241], v171 offset:36864
	ds_read_b64_tr_b16 v[242:243], v171 offset:38912
	ds_read_b64_tr_b16 v[252:253], v172 offset:36864
	ds_read_b64_tr_b16 v[254:255], v172 offset:38912
	v_mfma_f32_16x16x32_bf16 v[104:107], v[248:251], v[176:179], v[104:107]
	v_exp_f32_e32 v188, v188
	v_mfma_f32_16x16x32_bf16 v[88:91], v[248:251], v[192:195], v[88:91]
	v_exp_f32_e32 v189, v189
	v_mfma_f32_16x16x32_bf16 v[100:103], v[24:27], v[176:179], v[100:103]
	v_exp_f32_e32 v190, v190
	v_mfma_f32_16x16x32_bf16 v[80:83], v[24:27], v[192:195], v[80:83]
	v_exp_f32_e32 v191, v191
	v_mfma_f32_16x16x32_bf16 v[96:99], v[28:31], v[176:179], v[96:99]
	v_exp_f32_e32 v204, v204
	v_mfma_f32_16x16x32_bf16 v[76:79], v[28:31], v[192:195], v[76:79]
	v_exp_f32_e32 v205, v205
	s_waitcnt lgkmcnt(6)
	v_mfma_f32_16x16x32_bf16 v[124:127], v[4:7], v[8:11], v[108:111]
	v_exp_f32_e32 v206, v206
	v_exp_f32_e32 v207, v207
	v_mfma_f32_16x16x32_bf16 v[140:143], v[4:7], v[40:43], v[112:115]
	s_nop 0
	v_cvt_pk_bf16_f32 v184, v184, v185
	v_mfma_f32_16x16x32_bf16 v[124:127], v[12:15], v[32:35], v[124:127]
	v_cvt_pk_bf16_f32 v185, v186, v187
	v_cvt_pk_bf16_f32 v186, v188, v189
	v_mfma_f32_16x16x32_bf16 v[140:143], v[12:15], v[44:47], v[140:143]
	v_cvt_pk_bf16_f32 v187, v190, v191
	v_cvt_pk_bf16_f32 v200, v200, v201
	v_mfma_f32_16x16x32_bf16 v[124:127], v[20:23], v[36:39], v[124:127]
	v_cvt_pk_bf16_f32 v201, v202, v203
	v_cvt_pk_bf16_f32 v202, v204, v205
	v_mfma_f32_16x16x32_bf16 v[140:143], v[20:23], v[16:19], v[140:143]
	v_cvt_pk_bf16_f32 v203, v206, v207
	ds_read_b128 v[4:7], v175 offset:3072
	ds_read_b128 v[12:15], v175 offset:7168
	ds_read_b128 v[20:23], v175 offset:11264
	ds_read_b64_tr_b16 v[24:25], v173 offset:36864
	ds_read_b64_tr_b16 v[26:27], v173 offset:38912
	v_mfma_f32_16x16x32_bf16 v[92:95], v[148:151], v[176:179], v[92:95]
	v_mfma_f32_16x16x32_bf16 v[72:75], v[148:151], v[192:195], v[72:75]
	v_mfma_f32_16x16x32_bf16 v[84:87], v[152:155], v[176:179], v[84:87]
	v_mfma_f32_16x16x32_bf16 v[68:71], v[152:155], v[192:195], v[68:71]
	s_waitcnt lgkmcnt(2)
	v_mfma_f32_16x16x32_bf16 v[128:131], v[4:7], v[8:11], v[108:111]
	s_waitcnt vmcnt(0)
	v_mfma_f32_16x16x32_bf16 v[144:147], v[4:7], v[40:43], v[112:115]
	ds_write_b128 v168, v[56:59] offset:20480
	v_mfma_f32_16x16x32_bf16 v[128:131], v[12:15], v[32:35], v[128:131]
	ds_write_b128 v168, v[60:63] offset:22528
	v_mfma_f32_16x16x32_bf16 v[144:147], v[12:15], v[44:47], v[144:147]
	ds_write_b128 v169, v[52:55] offset:28672
	v_mfma_f32_16x16x32_bf16 v[128:131], v[20:23], v[36:39], v[128:131]
	ds_write_b128 v170, v[48:51] offset:12288
	v_mfma_f32_16x16x32_bf16 v[144:147], v[20:23], v[16:19], v[144:147]
	ds_write_b128 v170, v[64:67] offset:16384
	v_mfma_f32_16x16x32_bf16 v[104:107], v[248:251], v[184:187], v[104:107]
	global_load_dwordx4 v[48:51], v[164:165], off offset:128
	s_mov_b64 s[0:1], 0x10000
	v_lshl_add_u64 v[212:213], v[164:165], 0, s[0:1]
	global_load_dwordx4 v[64:67], v[212:213], off offset:128
	v_mfma_f32_16x16x32_bf16 v[88:91], v[248:251], v[200:203], v[88:91]
	s_mov_b64 s[0:1], 0x20000
	v_lshl_add_u64 v[164:165], v[164:165], 0, s[0:1]
	global_load_dwordx4 v[56:59], v[164:165], off
	s_mov_b64 s[0:1], 0x10000
	v_mfma_f32_16x16x32_bf16 v[100:103], v[208:211], v[184:187], v[100:103]
	v_lshl_add_u64 v[212:213], v[164:165], 0, s[0:1]
	global_load_dwordx4 v[60:63], v[212:213], off
	global_load_dwordx4 v[52:55], v[160:161], off
	s_mov_b64 s[0:1], 0xe4000
	v_mfma_f32_16x16x32_bf16 v[80:83], v[208:211], v[200:203], v[80:83]
	v_lshl_add_u64 v[160:161], v[160:161], 0, s[0:1]
	v_max3_f32 v2, v116, v117, v118
	v_max3_f32 v3, v132, v133, v134
	v_max3_f32 v2, v2, v119, v120
	v_mfma_f32_16x16x32_bf16 v[96:99], v[240:243], v[184:187], v[96:99]
	v_max3_f32 v3, v3, v135, v136
	v_max3_f32 v2, v2, v121, v122
	v_max3_f32 v3, v3, v137, v138
	v_max3_f32 v2, v2, v123, v124
	v_mfma_f32_16x16x32_bf16 v[76:79], v[240:243], v[200:203], v[76:79]
	v_max3_f32 v3, v3, v139, v140
	v_max3_f32 v2, v2, v125, v126
	v_max3_f32 v3, v3, v141, v142
	v_max3_f32 v2, v2, v127, v128
	v_mfma_f32_16x16x32_bf16 v[92:95], v[252:255], v[184:187], v[92:95]
	v_max3_f32 v3, v3, v143, v144
	v_max3_f32 v2, v2, v129, v130
	v_max3_f32 v3, v3, v145, v146
	v_max3_f32 v2, v2, v131, v131
	v_mfma_f32_16x16x32_bf16 v[72:75], v[252:255], v[200:203], v[72:75]
	v_max3_f32 v3, v3, v147, v147
	s_waitcnt lgkmcnt(0)
	v_mfma_f32_16x16x32_bf16 v[84:87], v[24:27], v[184:187], v[84:87]
	v_mfma_f32_16x16x32_bf16 v[68:71], v[24:27], v[200:203], v[68:71]
	s_add_i32 s57, s57, 1
	s_cmp_lt_u32 s57, s44
	s_barrier
	s_cbranch_scc1 .Lmla_x_body0

.Ltramp_anchor:
.Ltramp_BB0_8:
	s_branch .LBB0_8
.Ltramp_BB0_825:
	s_branch .LBB0_825
.Ltramp_BB0_896:
	s_branch .LBB0_896
.Ltramp_BB0_9:
	s_branch .LBB0_9
	s_branch .LBB0_440

	.amdhsa_kernel _Z11mega_kernel6Paramsii
		.amdhsa_group_segment_fixed_size 70400
		.amdhsa_private_segment_fixed_size 0
		.amdhsa_kernarg_size 456
		.amdhsa_user_sgpr_count 2
		.amdhsa_user_sgpr_dispatch_ptr 0
		.amdhsa_user_sgpr_queue_ptr 0
		.amdhsa_user_sgpr_kernarg_segment_ptr 1
		.amdhsa_user_sgpr_dispatch_id 0
		.amdhsa_user_sgpr_kernarg_preload_length 0
		.amdhsa_user_sgpr_kernarg_preload_offset 0
		.amdhsa_user_sgpr_private_segment_size 0
		.amdhsa_uses_dynamic_stack 0
		.amdhsa_enable_private_segment 0
		.amdhsa_system_sgpr_workgroup_id_x 1
		.amdhsa_system_sgpr_workgroup_id_y 0
		.amdhsa_system_sgpr_workgroup_id_z 0
		.amdhsa_system_sgpr_workgroup_info 0
		.amdhsa_system_vgpr_workitem_id 2
		.amdhsa_next_free_vgpr 256
		.amdhsa_next_free_sgpr 100
		.amdhsa_accum_offset 256
		.amdhsa_reserve_vcc 1
		.amdhsa_float_round_mode_32 0
		.amdhsa_float_round_mode_16_64 0
		.amdhsa_float_denorm_mode_32 3
		.amdhsa_float_denorm_mode_16_64 3
		.amdhsa_dx10_clamp 1
		.amdhsa_ieee_mode 1
		.amdhsa_fp16_overflow 0
		.amdhsa_tg_split 0
		.amdhsa_exception_fp_ieee_invalid_op 0
		.amdhsa_exception_fp_denorm_src 0
		.amdhsa_exception_fp_ieee_div_zero 0
		.amdhsa_exception_fp_ieee_overflow 0
		.amdhsa_exception_fp_ieee_underflow 0
		.amdhsa_exception_fp_ieee_inexact 0
		.amdhsa_exception_int_div_zero 0
	.end_amdhsa_kernel

amdhsa.kernels:
  - .agpr_count:     0
    .args:
      - .offset:         0
        .size:           192
        .value_kind:     by_value
      - .offset:         192
        .size:           4
        .value_kind:     by_value
      - .offset:         196
        .size:           4
        .value_kind:     by_value
      - .offset:         200
        .size:           4
        .value_kind:     hidden_block_count_x
      - .offset:         204
        .size:           4
        .value_kind:     hidden_block_count_y
      - .offset:         208
        .size:           4
        .value_kind:     hidden_block_count_z
      - .offset:         212
        .size:           2
        .value_kind:     hidden_group_size_x
      - .offset:         214
        .size:           2
        .value_kind:     hidden_group_size_y
      - .offset:         216
        .size:           2
        .value_kind:     hidden_group_size_z
      - .offset:         218
        .size:           2
        .value_kind:     hidden_remainder_x
      - .offset:         220
        .size:           2
        .value_kind:     hidden_remainder_y
      - .offset:         222
        .size:           2
        .value_kind:     hidden_remainder_z
      - .offset:         240
        .size:           8
        .value_kind:     hidden_global_offset_x
      - .offset:         248
        .size:           8
        .value_kind:     hidden_global_offset_y
      - .offset:         256
        .size:           8
        .value_kind:     hidden_global_offset_z
      - .offset:         264
        .size:           2
        .value_kind:     hidden_grid_dims
      - .offset:         288
        .size:           8
        .value_kind:     hidden_multigrid_sync_arg
    .group_segment_fixed_size: 70400
    .kernarg_segment_align: 8
    .kernarg_segment_size: 456
    .language:       OpenCL C
    .language_version:
      - 2
      - 0
    .max_flat_workgroup_size: 256
    .name:           _Z11mega_kernel6Paramsii
    .private_segment_fixed_size: 0
    .sgpr_count:     106
    .sgpr_spill_count: 281
    .symbol:         _Z11mega_kernel6Paramsii.kd
    .uniform_work_group_size: 1
    .uses_dynamic_stack: false
    .vgpr_count:     256
    .vgpr_spill_count: 0
    .wavefront_size: 64
